# hand-written conv31+LN+swish phase: register sliding window, all 31 taps resident, no LDS ring; on top of fused W_o epilogue
# speedup vs baseline: 1.0394x; 1.0178x over previous
; #define LAS __attribute__((address_space(3)))
; __device__ __forceinline__ int tid_of(int widx) { int l; asm volatile("v_mbcnt_lo_u32_b32 %0, -1, 0\n\tv_mbcnt_hi_u32_b32 %0, -1, %0" : "=v"(l)); return widx * 64 + l; }
; template <int PH> ...
;     ...
;     const f32x2 bias = *(const f32x2*)(cb + c2);
;     f32x2 outv[16];
; #pragma unroll
;     for (int t = 0; t < 16; ++t) outv[t] = bias;
; #pragma unroll
;     for (int ps = 0; ps < 2; ++ps) {
;         const int kb = ps * 16, ntap = ps == 0 ? 16 : 15;
;         f32x2 w[16];
; #pragma unroll
;         for (int k = 0; k < 16; ++k) if (k < ntap) w[k] = *(const f32x2*)(cw + (kb + k) * 1024 + c2);
; __device__ __forceinline__ void conv31_phase(LAS unsigned char* lds, const bf16_t* GLU, bf16_t* SZB, const float* cw, const float* cb, const float* lng, const float* lnb, int G, int c, const int widx) {
;     int tid_ = tid_of(widx); asm volatile("" : "+v"(tid_));
;     const int tid = tid_;
;     LAS float* red = (LAS float*)(lds + 131072 + 1024);
;     LAS float* stats = (LAS float*)(lds + 131072 + 3072);
;     for (int run = c; run < NTOK / 128; run += G) {
;         const int T0 = run * 128, tpos = T0 & (SEQ - 1);
;         __syncthreads();
; #pragma unroll
;         for (int h = 0; h < 2; ++h) {
;             int tf = tid; asm volatile("" : "+v"(tf));
;             u32x4 tv[6];
; #pragma unroll
;             for (int q = 0; q < 6; ++q) { const int i = tf + (h * 6 + q) * 512, r = (i >> 7) < 46 ? (i >> 7) : 45; const int gr = (tpos - 30 + r >= 0) ? (T0 - 30 + r) : T0;
;                 tv[q] = *(const u32x4*)(GLU + (size_t)gr * 1024 + (i & 127) * 8); }
; #pragma unroll
;             for (int q = 0; q < 6; ++q) { const int i = tf + (h * 6 + q) * 512, r = i >> 7;
;                 if (r < 46) *(LAS u32x4*)(lds + ((34 + r) & 63) * 2048 + (i & 127) * 16) = (tpos - 30 + r >= 0) ? tv[q] : (u32x4){0u, 0u, 0u, 0u}; }
;         }
;         __syncthreads();
.LBB0_385:
	v_mbcnt_lo_u32_b32 v224, -1, 0
	v_mbcnt_hi_u32_b32 v224, -1, v224
	s_cmpk_gt_i32 s2, 0xff
	s_cbranch_scc1 .LBB0_458
	v_add_u32_e32 v225, s87, v224
	v_lshlrev_b32_e32 v226, 2, v225
	v_lshlrev_b32_e32 v227, 3, v225
	v_mov_b32_e32 v254, 0
	v_lshrrev_b32_e32 v253, 4, v224
	v_lshlrev_b32_e32 v253, 7, v253
	s_lshr_b32 s4, s87, 3
	v_add_u32_e32 v253, s4, v253
	s_lshl_b32 s6, s2, 7
	s_mov_b32 s54, 0xbfb8aa3b
	s_mov_b32 s55, 0xbfb8aa3b
	s_mov_b64 s[100:101], s[48:49]
	global_load_dwordx2 v[92:93], v227, s[100:101]
	s_add_u32 s100, s100, 0x1000
	s_addc_u32 s101, s101, 0
	global_load_dwordx2 v[94:95], v227, s[100:101]
	s_add_u32 s100, s100, 0x1000
	s_addc_u32 s101, s101, 0
	global_load_dwordx2 v[96:97], v227, s[100:101]
	s_add_u32 s100, s100, 0x1000
	s_addc_u32 s101, s101, 0
	global_load_dwordx2 v[98:99], v227, s[100:101]
	s_add_u32 s100, s100, 0x1000
	s_addc_u32 s101, s101, 0
	global_load_dwordx2 v[100:101], v227, s[100:101]
	s_add_u32 s100, s100, 0x1000
	s_addc_u32 s101, s101, 0
	global_load_dwordx2 v[102:103], v227, s[100:101]
	s_add_u32 s100, s100, 0x1000
	s_addc_u32 s101, s101, 0
	global_load_dwordx2 v[104:105], v227, s[100:101]
	s_add_u32 s100, s100, 0x1000
	s_addc_u32 s101, s101, 0
	global_load_dwordx2 v[106:107], v227, s[100:101]
	s_add_u32 s100, s100, 0x1000
	s_addc_u32 s101, s101, 0
	global_load_dwordx2 v[108:109], v227, s[100:101]
	s_add_u32 s100, s100, 0x1000
	s_addc_u32 s101, s101, 0
	global_load_dwordx2 v[110:111], v227, s[100:101]
	s_add_u32 s100, s100, 0x1000
	s_addc_u32 s101, s101, 0
	global_load_dwordx2 v[112:113], v227, s[100:101]
	s_add_u32 s100, s100, 0x1000
	s_addc_u32 s101, s101, 0
	global_load_dwordx2 v[114:115], v227, s[100:101]
	s_add_u32 s100, s100, 0x1000
	s_addc_u32 s101, s101, 0
	global_load_dwordx2 v[116:117], v227, s[100:101]
	s_add_u32 s100, s100, 0x1000
	s_addc_u32 s101, s101, 0
	global_load_dwordx2 v[118:119], v227, s[100:101]
	s_add_u32 s100, s100, 0x1000
	s_addc_u32 s101, s101, 0
	global_load_dwordx2 v[120:121], v227, s[100:101]
	s_add_u32 s100, s100, 0x1000
	s_addc_u32 s101, s101, 0
	global_load_dwordx2 v[122:123], v227, s[100:101]
	s_add_u32 s100, s100, 0x1000
	s_addc_u32 s101, s101, 0
	global_load_dwordx2 v[124:125], v227, s[100:101]
	s_add_u32 s100, s100, 0x1000
	s_addc_u32 s101, s101, 0
	global_load_dwordx2 v[126:127], v227, s[100:101]
	s_add_u32 s100, s100, 0x1000
	s_addc_u32 s101, s101, 0
	global_load_dwordx2 v[128:129], v227, s[100:101]
	s_add_u32 s100, s100, 0x1000
	s_addc_u32 s101, s101, 0
	global_load_dwordx2 v[130:131], v227, s[100:101]
	s_add_u32 s100, s100, 0x1000
	s_addc_u32 s101, s101, 0
	global_load_dwordx2 v[132:133], v227, s[100:101]
	s_add_u32 s100, s100, 0x1000
	s_addc_u32 s101, s101, 0
	global_load_dwordx2 v[134:135], v227, s[100:101]
	s_add_u32 s100, s100, 0x1000
	s_addc_u32 s101, s101, 0
	global_load_dwordx2 v[136:137], v227, s[100:101]
	s_add_u32 s100, s100, 0x1000
	s_addc_u32 s101, s101, 0
	global_load_dwordx2 v[138:139], v227, s[100:101]
	s_add_u32 s100, s100, 0x1000
	s_addc_u32 s101, s101, 0
	global_load_dwordx2 v[140:141], v227, s[100:101]
	s_add_u32 s100, s100, 0x1000
	s_addc_u32 s101, s101, 0
	global_load_dwordx2 v[142:143], v227, s[100:101]
	s_add_u32 s100, s100, 0x1000
	s_addc_u32 s101, s101, 0
	global_load_dwordx2 v[144:145], v227, s[100:101]
	s_add_u32 s100, s100, 0x1000
	s_addc_u32 s101, s101, 0
	global_load_dwordx2 v[146:147], v227, s[100:101]
	s_add_u32 s100, s100, 0x1000
	s_addc_u32 s101, s101, 0
	global_load_dwordx2 v[148:149], v227, s[100:101]
	s_add_u32 s100, s100, 0x1000
	s_addc_u32 s101, s101, 0
	global_load_dwordx2 v[150:151], v227, s[100:101]
	s_add_u32 s100, s100, 0x1000
	s_addc_u32 s101, s101, 0
	global_load_dwordx2 v[152:153], v227, s[100:101]
	global_load_dwordx2 v[218:219], v227, s[50:51]
	global_load_dwordx2 v[220:221], v227, s[8:9]
	global_load_dwordx2 v[222:223], v227, s[10:11]
	s_and_b32 s4, s6, 0x1fff
	s_cmp_eq_u32 s4, 0
	s_cbranch_scc1 .Lc31_seqstart
	s_sub_i32 s100, s6, 30
	s_ashr_i32 s101, s100, 31
	s_lshl_b64 s[100:101], s[100:101], 11
	s_add_u32 s100, s100, s14
	s_addc_u32 s101, s101, s15
	global_load_dword v0, v226, s[100:101]
	global_load_dword v2, v226, s[100:101] offset:2048
	s_add_u32 s100, s100, 0x1000
	s_addc_u32 s101, s101, 0
	global_load_dword v4, v226, s[100:101]
	global_load_dword v6, v226, s[100:101] offset:2048
	s_add_u32 s100, s100, 0x1000
	s_addc_u32 s101, s101, 0
	global_load_dword v8, v226, s[100:101]
	global_load_dword v10, v226, s[100:101] offset:2048
	s_add_u32 s100, s100, 0x1000
	s_addc_u32 s101, s101, 0
	global_load_dword v12, v226, s[100:101]
	global_load_dword v14, v226, s[100:101] offset:2048
	s_add_u32 s100, s100, 0x1000
	s_addc_u32 s101, s101, 0
	global_load_dword v16, v226, s[100:101]
	global_load_dword v18, v226, s[100:101] offset:2048
	s_add_u32 s100, s100, 0x1000
	s_addc_u32 s101, s101, 0
	global_load_dword v20, v226, s[100:101]
	global_load_dword v22, v226, s[100:101] offset:2048
	s_add_u32 s100, s100, 0x1000
	s_addc_u32 s101, s101, 0
	global_load_dword v24, v226, s[100:101]
	global_load_dword v26, v226, s[100:101] offset:2048
	s_add_u32 s100, s100, 0x1000
	s_addc_u32 s101, s101, 0
	global_load_dword v28, v226, s[100:101]
	global_load_dword v30, v226, s[100:101] offset:2048
	s_add_u32 s100, s100, 0x1000
	s_addc_u32 s101, s101, 0
	global_load_dword v32, v226, s[100:101]
	global_load_dword v34, v226, s[100:101] offset:2048
	s_add_u32 s100, s100, 0x1000
	s_addc_u32 s101, s101, 0
	global_load_dword v36, v226, s[100:101]
	global_load_dword v38, v226, s[100:101] offset:2048
	s_add_u32 s100, s100, 0x1000
	s_addc_u32 s101, s101, 0
	global_load_dword v40, v226, s[100:101]
	global_load_dword v42, v226, s[100:101] offset:2048
; #define LAS __attribute__((address_space(3)))
; __device__ __forceinline__ void conv31_phase(LAS unsigned char* lds, const bf16_t* GLU, bf16_t* SZB, const float* cw, const float* cb, const float* lng, const float* lnb, int G, int c, const int widx) {
;     ...
;     for (int run = c; run < NTOK / 128; run += G) {
;         const int T0 = run * 128, tpos = T0 & (SEQ - 1);
;         __syncthreads();
; #pragma unroll
;         for (int h = 0; h < 2; ++h) {
;             int tf = tid; asm volatile("" : "+v"(tf));
;             u32x4 tv[6];
; #pragma unroll
;             for (int q = 0; q < 6; ++q) { const int i = tf + (h * 6 + q) * 512, r = (i >> 7) < 46 ? (i >> 7) : 45; const int gr = (tpos - 30 + r >= 0) ? (T0 - 30 + r) : T0;
;                 tv[q] = *(const u32x4*)(GLU + (size_t)gr * 1024 + (i & 127) * 8); }
; #pragma unroll
;             for (int q = 0; q < 6; ++q) { const int i = tf + (h * 6 + q) * 512, r = i >> 7;
;                 if (r < 46) *(LAS u32x4*)(lds + ((34 + r) & 63) * 2048 + (i & 127) * 16) = (tpos - 30 + r >= 0) ? tv[q] : (u32x4){0u, 0u, 0u, 0u}; }
;         }
;         __syncthreads();
	s_add_u32 s100, s100, 0x1000
	s_addc_u32 s101, s101, 0
	global_load_dword v44, v226, s[100:101]
	global_load_dword v46, v226, s[100:101] offset:2048
	s_add_u32 s100, s100, 0x1000
	s_addc_u32 s101, s101, 0
	global_load_dword v48, v226, s[100:101]
	global_load_dword v50, v226, s[100:101] offset:2048
	s_add_u32 s100, s100, 0x1000
	s_addc_u32 s101, s101, 0
	global_load_dword v52, v226, s[100:101]
	global_load_dword v54, v226, s[100:101] offset:2048
	s_add_u32 s100, s100, 0x1000
	s_addc_u32 s101, s101, 0
	global_load_dword v56, v226, s[100:101]
	global_load_dword v58, v226, s[100:101] offset:2048
	s_add_u32 s100, s100, 0x1000
	s_addc_u32 s101, s101, 0
	global_load_dword v60, v226, s[100:101]
	global_load_dword v62, v226, s[100:101] offset:2048
	s_add_u32 s100, s100, 0x1000
	s_addc_u32 s101, s101, 0
	global_load_dword v64, v226, s[100:101]
	global_load_dword v66, v226, s[100:101] offset:2048
	s_add_u32 s100, s100, 0x1000
	s_addc_u32 s101, s101, 0
	global_load_dword v68, v226, s[100:101]
	global_load_dword v70, v226, s[100:101] offset:2048
	s_add_u32 s100, s100, 0x1000
	s_addc_u32 s101, s101, 0
	global_load_dword v72, v226, s[100:101]
	global_load_dword v74, v226, s[100:101] offset:2048
	s_add_u32 s100, s100, 0x1000
	s_addc_u32 s101, s101, 0
	global_load_dword v76, v226, s[100:101]
	global_load_dword v78, v226, s[100:101] offset:2048
	s_add_u32 s100, s100, 0x1000
	s_addc_u32 s101, s101, 0
	global_load_dword v80, v226, s[100:101]
	global_load_dword v82, v226, s[100:101] offset:2048
	s_add_u32 s100, s100, 0x1000
	s_addc_u32 s101, s101, 0
	global_load_dword v84, v226, s[100:101]
	global_load_dword v86, v226, s[100:101] offset:2048
	s_add_u32 s100, s100, 0x1000
	s_addc_u32 s101, s101, 0
	global_load_dword v88, v226, s[100:101]
	global_load_dword v90, v226, s[100:101] offset:2048
	s_branch .Lc31_filled
.Lc31_seqstart:
	v_mov_b32_e32 v0, 0
	v_mov_b32_e32 v2, 0
	v_mov_b32_e32 v4, 0
	v_mov_b32_e32 v6, 0
	v_mov_b32_e32 v8, 0
	v_mov_b32_e32 v10, 0
	v_mov_b32_e32 v12, 0
	v_mov_b32_e32 v14, 0
	v_mov_b32_e32 v16, 0
	v_mov_b32_e32 v18, 0
	v_mov_b32_e32 v20, 0
	v_mov_b32_e32 v22, 0
	v_mov_b32_e32 v24, 0
	v_mov_b32_e32 v26, 0
	v_mov_b32_e32 v28, 0
	v_mov_b32_e32 v30, 0
	v_mov_b32_e32 v32, 0
	v_mov_b32_e32 v34, 0
	v_mov_b32_e32 v36, 0
	v_mov_b32_e32 v38, 0
	v_mov_b32_e32 v40, 0
	v_mov_b32_e32 v42, 0
	v_mov_b32_e32 v44, 0
	v_mov_b32_e32 v46, 0
	v_mov_b32_e32 v48, 0
	v_mov_b32_e32 v50, 0
	v_mov_b32_e32 v52, 0
	v_mov_b32_e32 v54, 0
	v_mov_b32_e32 v56, 0
	v_mov_b32_e32 v58, 0
	s_ashr_i32 s7, s6, 31
	s_lshl_b64 s[100:101], s[6:7], 11
	s_add_u32 s100, s100, s14
	s_addc_u32 s101, s101, s15
	global_load_dword v60, v226, s[100:101]
	global_load_dword v62, v226, s[100:101] offset:2048
	s_add_u32 s100, s100, 0x1000
	s_addc_u32 s101, s101, 0
	global_load_dword v64, v226, s[100:101]
	global_load_dword v66, v226, s[100:101] offset:2048
	s_add_u32 s100, s100, 0x1000
	s_addc_u32 s101, s101, 0
	global_load_dword v68, v226, s[100:101]
	global_load_dword v70, v226, s[100:101] offset:2048
	s_add_u32 s100, s100, 0x1000
	s_addc_u32 s101, s101, 0
	global_load_dword v72, v226, s[100:101]
	global_load_dword v74, v226, s[100:101] offset:2048
	s_add_u32 s100, s100, 0x1000
	s_addc_u32 s101, s101, 0
	global_load_dword v76, v226, s[100:101]
	global_load_dword v78, v226, s[100:101] offset:2048
	s_add_u32 s100, s100, 0x1000
	s_addc_u32 s101, s101, 0
	global_load_dword v80, v226, s[100:101]
	global_load_dword v82, v226, s[100:101] offset:2048
	s_add_u32 s100, s100, 0x1000
	s_addc_u32 s101, s101, 0
	global_load_dword v84, v226, s[100:101]
	global_load_dword v86, v226, s[100:101] offset:2048
	s_add_u32 s100, s100, 0x1000
	s_addc_u32 s101, s101, 0
	global_load_dword v88, v226, s[100:101]
	global_load_dword v90, v226, s[100:101] offset:2048
.Lc31_filled:
	s_waitcnt vmcnt(0)
	v_and_b32_e32 v1, 0xffff0000, v0
	v_lshlrev_b32_e32 v0, 16, v0
	v_and_b32_e32 v3, 0xffff0000, v2
	v_lshlrev_b32_e32 v2, 16, v2
	v_and_b32_e32 v5, 0xffff0000, v4
	v_lshlrev_b32_e32 v4, 16, v4
	v_and_b32_e32 v7, 0xffff0000, v6
	v_lshlrev_b32_e32 v6, 16, v6
	v_and_b32_e32 v9, 0xffff0000, v8
	v_lshlrev_b32_e32 v8, 16, v8
	v_and_b32_e32 v11, 0xffff0000, v10
	v_lshlrev_b32_e32 v10, 16, v10
	v_and_b32_e32 v13, 0xffff0000, v12
	v_lshlrev_b32_e32 v12, 16, v12
	v_and_b32_e32 v15, 0xffff0000, v14
	v_lshlrev_b32_e32 v14, 16, v14
	v_and_b32_e32 v17, 0xffff0000, v16
	v_lshlrev_b32_e32 v16, 16, v16
	v_and_b32_e32 v19, 0xffff0000, v18
	v_lshlrev_b32_e32 v18, 16, v18
	v_and_b32_e32 v21, 0xffff0000, v20
	v_lshlrev_b32_e32 v20, 16, v20
	v_and_b32_e32 v23, 0xffff0000, v22
	v_lshlrev_b32_e32 v22, 16, v22
	v_and_b32_e32 v25, 0xffff0000, v24
	v_lshlrev_b32_e32 v24, 16, v24
	v_and_b32_e32 v27, 0xffff0000, v26
	v_lshlrev_b32_e32 v26, 16, v26
	v_and_b32_e32 v29, 0xffff0000, v28
	v_lshlrev_b32_e32 v28, 16, v28
	v_and_b32_e32 v31, 0xffff0000, v30
	v_lshlrev_b32_e32 v30, 16, v30
	v_and_b32_e32 v33, 0xffff0000, v32
	v_lshlrev_b32_e32 v32, 16, v32
	v_and_b32_e32 v35, 0xffff0000, v34
	v_lshlrev_b32_e32 v34, 16, v34
	v_and_b32_e32 v37, 0xffff0000, v36
	v_lshlrev_b32_e32 v36, 16, v36
	v_and_b32_e32 v39, 0xffff0000, v38
	v_lshlrev_b32_e32 v38, 16, v38
	v_and_b32_e32 v41, 0xffff0000, v40
	v_lshlrev_b32_e32 v40, 16, v40
	v_and_b32_e32 v43, 0xffff0000, v42
	v_lshlrev_b32_e32 v42, 16, v42
	v_and_b32_e32 v45, 0xffff0000, v44
	v_lshlrev_b32_e32 v44, 16, v44
	v_and_b32_e32 v47, 0xffff0000, v46
	v_lshlrev_b32_e32 v46, 16, v46
	v_and_b32_e32 v49, 0xffff0000, v48
	v_lshlrev_b32_e32 v48, 16, v48
	v_and_b32_e32 v51, 0xffff0000, v50
	v_lshlrev_b32_e32 v50, 16, v50
	v_and_b32_e32 v53, 0xffff0000, v52
	v_lshlrev_b32_e32 v52, 16, v52
	v_and_b32_e32 v55, 0xffff0000, v54
	v_lshlrev_b32_e32 v54, 16, v54
	v_and_b32_e32 v57, 0xffff0000, v56
	v_lshlrev_b32_e32 v56, 16, v56
	v_and_b32_e32 v59, 0xffff0000, v58
	v_lshlrev_b32_e32 v58, 16, v58
	v_and_b32_e32 v61, 0xffff0000, v60
	v_lshlrev_b32_e32 v60, 16, v60
	v_and_b32_e32 v63, 0xffff0000, v62
	v_lshlrev_b32_e32 v62, 16, v62
	v_and_b32_e32 v65, 0xffff0000, v64
	v_lshlrev_b32_e32 v64, 16, v64
	v_and_b32_e32 v67, 0xffff0000, v66
	v_lshlrev_b32_e32 v66, 16, v66
	v_and_b32_e32 v69, 0xffff0000, v68
	v_lshlrev_b32_e32 v68, 16, v68
	v_and_b32_e32 v71, 0xffff0000, v70
	v_lshlrev_b32_e32 v70, 16, v70
	v_and_b32_e32 v73, 0xffff0000, v72
	v_lshlrev_b32_e32 v72, 16, v72
	v_and_b32_e32 v75, 0xffff0000, v74
	v_lshlrev_b32_e32 v74, 16, v74
	v_and_b32_e32 v77, 0xffff0000, v76
	v_lshlrev_b32_e32 v76, 16, v76
	v_and_b32_e32 v79, 0xffff0000, v78
	v_lshlrev_b32_e32 v78, 16, v78
	v_and_b32_e32 v81, 0xffff0000, v80
	v_lshlrev_b32_e32 v80, 16, v80
	v_and_b32_e32 v83, 0xffff0000, v82
	v_lshlrev_b32_e32 v82, 16, v82
	v_and_b32_e32 v85, 0xffff0000, v84
	v_lshlrev_b32_e32 v84, 16, v84
	v_and_b32_e32 v87, 0xffff0000, v86
	v_lshlrev_b32_e32 v86, 16, v86
	v_and_b32_e32 v89, 0xffff0000, v88
	v_lshlrev_b32_e32 v88, 16, v88
	v_and_b32_e32 v91, 0xffff0000, v90
	v_lshlrev_b32_e32 v90, 16, v90
	s_mov_b32 s7, 0
	s_mov_b32 s34, s6
; #define LAS __attribute__((address_space(3)))
; __device__ __forceinline__ float bf_lo(unsigned u) { return __uint_as_float(u << 16); }
; __device__ __forceinline__ float bf_hi(unsigned u) { return __uint_as_float(u & 0xffff0000u); }
; template <int PH> ...
;     ...
;     if (has_next) {
;         int tf = tid; asm volatile("" : "+v"(tf));
; #pragma unroll
;         for (int q = 0; q < 4; ++q) { const int i = tf + q * 512; nx[q] = __builtin_nontemporal_load((const u32x4*)(GLU + (size_t)(t0 + 16 + (i >> 7)) * 1024 + (i & 127) * 8)); }
;     }
;     const f32x2 bias = *(const f32x2*)(cb + c2);
;     f32x2 outv[16];
; #pragma unroll
;     for (int t = 0; t < 16; ++t) outv[t] = bias;
;     ...
;         for (int r = 0; r < 31; ++r) if (r < ntap + 15) {
;             const unsigned v = *(const LAS unsigned*)(lds + ((34 + 16 * PH + kb + r) & 63) * 2048 + tid * 4);
;             const f32x2 x = (f32x2){bf_lo(v), bf_hi(v)};
; #pragma unroll
;             for (int t = 0; t < 16; ++t) { const int k = r - t; if (k >= 0 && k < ntap) outv[t] = __builtin_elementwise_fma(w[k], x, outv[t]); }
.Lc31_chunk:
	s_ashr_i32 s35, s34, 31
	s_lshl_b64 s[28:29], s[34:35], 11
	s_add_u32 s100, s28, s52
	s_addc_u32 s101, s29, s53
	global_load_dword v202, v226, s[100:101] nt
	global_load_dword v203, v226, s[100:101] offset:2048 nt
	s_add_u32 s100, s100, 0x1000
	s_addc_u32 s101, s101, 0
	global_load_dword v204, v226, s[100:101] nt
	global_load_dword v205, v226, s[100:101] offset:2048 nt
	s_add_u32 s100, s100, 0x1000
	s_addc_u32 s101, s101, 0
	global_load_dword v206, v226, s[100:101] nt
	global_load_dword v207, v226, s[100:101] offset:2048 nt
	s_add_u32 s100, s100, 0x1000
	s_addc_u32 s101, s101, 0
	global_load_dword v208, v226, s[100:101] nt
	global_load_dword v209, v226, s[100:101] offset:2048 nt
	s_add_u32 s100, s100, 0x1000
	s_addc_u32 s101, s101, 0
	global_load_dword v210, v226, s[100:101] nt
	global_load_dword v211, v226, s[100:101] offset:2048 nt
	s_add_u32 s100, s100, 0x1000
	s_addc_u32 s101, s101, 0
	global_load_dword v212, v226, s[100:101] nt
	global_load_dword v213, v226, s[100:101] offset:2048 nt
	s_add_u32 s100, s100, 0x1000
	s_addc_u32 s101, s101, 0
	global_load_dword v214, v226, s[100:101] nt
	global_load_dword v215, v226, s[100:101] offset:2048 nt
	s_add_u32 s100, s100, 0x1000
	s_addc_u32 s101, s101, 0
	global_load_dword v216, v226, s[100:101] nt
	global_load_dword v217, v226, s[100:101] offset:2048 nt
	s_cmp_eq_u32 s7, 7
	s_cbranch_scc1 .Lc31_nonx
	s_add_u32 s100, s28, s14
	s_addc_u32 s101, s29, s15
	s_add_u32 s100, s100, 0x8000
	s_addc_u32 s101, s101, 0
	global_load_dword v186, v226, s[100:101] nt
	global_load_dword v187, v226, s[100:101] offset:2048 nt
	s_add_u32 s100, s100, 0x1000
	s_addc_u32 s101, s101, 0
	global_load_dword v188, v226, s[100:101] nt
	global_load_dword v189, v226, s[100:101] offset:2048 nt
	s_add_u32 s100, s100, 0x1000
	s_addc_u32 s101, s101, 0
	global_load_dword v190, v226, s[100:101] nt
	global_load_dword v191, v226, s[100:101] offset:2048 nt
	s_add_u32 s100, s100, 0x1000
	s_addc_u32 s101, s101, 0
	global_load_dword v192, v226, s[100:101] nt
	global_load_dword v193, v226, s[100:101] offset:2048 nt
	s_add_u32 s100, s100, 0x1000
	s_addc_u32 s101, s101, 0
	global_load_dword v194, v226, s[100:101] nt
	global_load_dword v195, v226, s[100:101] offset:2048 nt
	s_add_u32 s100, s100, 0x1000
	s_addc_u32 s101, s101, 0
	global_load_dword v196, v226, s[100:101] nt
	global_load_dword v197, v226, s[100:101] offset:2048 nt
	s_add_u32 s100, s100, 0x1000
	s_addc_u32 s101, s101, 0
	global_load_dword v198, v226, s[100:101] nt
	global_load_dword v199, v226, s[100:101] offset:2048 nt
	s_add_u32 s100, s100, 0x1000
	s_addc_u32 s101, s101, 0
	global_load_dword v200, v226, s[100:101] nt
	global_load_dword v201, v226, s[100:101] offset:2048 nt
.Lc31_nonx:
	s_nop 0
	s_cmp_lg_u32 s7, 0
	s_cbranch_scc1 .Lc31_wok
	s_waitcnt vmcnt(0)
.Lc31_wok:
	v_mov_b64_e32 v[154:155], v[218:219]
	v_mov_b64_e32 v[156:157], v[218:219]
	v_mov_b64_e32 v[158:159], v[218:219]
	v_mov_b64_e32 v[160:161], v[218:219]
	v_mov_b64_e32 v[162:163], v[218:219]
	v_mov_b64_e32 v[164:165], v[218:219]
	v_mov_b64_e32 v[166:167], v[218:219]
	v_mov_b64_e32 v[168:169], v[218:219]
	v_mov_b64_e32 v[170:171], v[218:219]
	v_mov_b64_e32 v[172:173], v[218:219]
	v_mov_b64_e32 v[174:175], v[218:219]
	v_mov_b64_e32 v[176:177], v[218:219]
	v_mov_b64_e32 v[178:179], v[218:219]
	v_mov_b64_e32 v[180:181], v[218:219]
	v_mov_b64_e32 v[182:183], v[218:219]
	v_mov_b64_e32 v[184:185], v[218:219]
	v_pk_fma_f32 v[154:155], v[92:93], v[0:1], v[154:155]
	v_pk_fma_f32 v[154:155], v[94:95], v[2:3], v[154:155]
	v_pk_fma_f32 v[156:157], v[92:93], v[2:3], v[156:157]
	v_pk_fma_f32 v[154:155], v[96:97], v[4:5], v[154:155]
	v_pk_fma_f32 v[156:157], v[94:95], v[4:5], v[156:157]
	v_pk_fma_f32 v[158:159], v[92:93], v[4:5], v[158:159]
	v_pk_fma_f32 v[154:155], v[98:99], v[6:7], v[154:155]
	v_pk_fma_f32 v[156:157], v[96:97], v[6:7], v[156:157]
	v_pk_fma_f32 v[158:159], v[94:95], v[6:7], v[158:159]
	v_pk_fma_f32 v[160:161], v[92:93], v[6:7], v[160:161]
	v_pk_fma_f32 v[154:155], v[100:101], v[8:9], v[154:155]
	v_pk_fma_f32 v[156:157], v[98:99], v[8:9], v[156:157]
	v_pk_fma_f32 v[158:159], v[96:97], v[8:9], v[158:159]
	v_pk_fma_f32 v[160:161], v[94:95], v[8:9], v[160:161]
	v_pk_fma_f32 v[162:163], v[92:93], v[8:9], v[162:163]
	v_pk_fma_f32 v[154:155], v[102:103], v[10:11], v[154:155]
	v_pk_fma_f32 v[156:157], v[100:101], v[10:11], v[156:157]
	v_pk_fma_f32 v[158:159], v[98:99], v[10:11], v[158:159]
	v_pk_fma_f32 v[160:161], v[96:97], v[10:11], v[160:161]
	v_pk_fma_f32 v[162:163], v[94:95], v[10:11], v[162:163]
	v_pk_fma_f32 v[164:165], v[92:93], v[10:11], v[164:165]
	v_pk_fma_f32 v[154:155], v[104:105], v[12:13], v[154:155]
	v_pk_fma_f32 v[156:157], v[102:103], v[12:13], v[156:157]
	v_pk_fma_f32 v[158:159], v[100:101], v[12:13], v[158:159]
	v_pk_fma_f32 v[160:161], v[98:99], v[12:13], v[160:161]
	v_pk_fma_f32 v[162:163], v[96:97], v[12:13], v[162:163]
	v_pk_fma_f32 v[164:165], v[94:95], v[12:13], v[164:165]
	v_pk_fma_f32 v[166:167], v[92:93], v[12:13], v[166:167]
	v_pk_fma_f32 v[154:155], v[106:107], v[14:15], v[154:155]
	v_pk_fma_f32 v[156:157], v[104:105], v[14:15], v[156:157]
	v_pk_fma_f32 v[158:159], v[102:103], v[14:15], v[158:159]
	v_pk_fma_f32 v[160:161], v[100:101], v[14:15], v[160:161]
	v_pk_fma_f32 v[162:163], v[98:99], v[14:15], v[162:163]
	v_pk_fma_f32 v[164:165], v[96:97], v[14:15], v[164:165]
	v_pk_fma_f32 v[166:167], v[94:95], v[14:15], v[166:167]
	v_pk_fma_f32 v[168:169], v[92:93], v[14:15], v[168:169]
	v_pk_fma_f32 v[154:155], v[108:109], v[16:17], v[154:155]
	v_pk_fma_f32 v[156:157], v[106:107], v[16:17], v[156:157]
	v_pk_fma_f32 v[158:159], v[104:105], v[16:17], v[158:159]
; #define LAS __attribute__((address_space(3)))
; __device__ __forceinline__ float bf_lo(unsigned u) { return __uint_as_float(u << 16); }
; __device__ __forceinline__ float bf_hi(unsigned u) { return __uint_as_float(u & 0xffff0000u); }
; template <int PH> ...
;     ...
;         for (int r = 0; r < 31; ++r) if (r < ntap + 15) {
;             const unsigned v = *(const LAS unsigned*)(lds + ((34 + 16 * PH + kb + r) & 63) * 2048 + tid * 4);
;             const f32x2 x = (f32x2){bf_lo(v), bf_hi(v)};
; #pragma unroll
;             for (int t = 0; t < 16; ++t) { const int k = r - t; if (k >= 0 && k < ntap) outv[t] = __builtin_elementwise_fma(w[k], x, outv[t]); }
	v_pk_fma_f32 v[160:161], v[102:103], v[16:17], v[160:161]
	v_pk_fma_f32 v[162:163], v[100:101], v[16:17], v[162:163]
	v_pk_fma_f32 v[164:165], v[98:99], v[16:17], v[164:165]
	v_pk_fma_f32 v[166:167], v[96:97], v[16:17], v[166:167]
	v_pk_fma_f32 v[168:169], v[94:95], v[16:17], v[168:169]
	v_pk_fma_f32 v[170:171], v[92:93], v[16:17], v[170:171]
	v_pk_fma_f32 v[154:155], v[110:111], v[18:19], v[154:155]
	v_pk_fma_f32 v[156:157], v[108:109], v[18:19], v[156:157]
	v_pk_fma_f32 v[158:159], v[106:107], v[18:19], v[158:159]
	v_pk_fma_f32 v[160:161], v[104:105], v[18:19], v[160:161]
	v_pk_fma_f32 v[162:163], v[102:103], v[18:19], v[162:163]
	v_pk_fma_f32 v[164:165], v[100:101], v[18:19], v[164:165]
	v_pk_fma_f32 v[166:167], v[98:99], v[18:19], v[166:167]
	v_pk_fma_f32 v[168:169], v[96:97], v[18:19], v[168:169]
	v_pk_fma_f32 v[170:171], v[94:95], v[18:19], v[170:171]
	v_pk_fma_f32 v[172:173], v[92:93], v[18:19], v[172:173]
	v_pk_fma_f32 v[154:155], v[112:113], v[20:21], v[154:155]
	v_pk_fma_f32 v[156:157], v[110:111], v[20:21], v[156:157]
	v_pk_fma_f32 v[158:159], v[108:109], v[20:21], v[158:159]
	v_pk_fma_f32 v[160:161], v[106:107], v[20:21], v[160:161]
	v_pk_fma_f32 v[162:163], v[104:105], v[20:21], v[162:163]
	v_pk_fma_f32 v[164:165], v[102:103], v[20:21], v[164:165]
	v_pk_fma_f32 v[166:167], v[100:101], v[20:21], v[166:167]
	v_pk_fma_f32 v[168:169], v[98:99], v[20:21], v[168:169]
	v_pk_fma_f32 v[170:171], v[96:97], v[20:21], v[170:171]
	v_pk_fma_f32 v[172:173], v[94:95], v[20:21], v[172:173]
	v_pk_fma_f32 v[174:175], v[92:93], v[20:21], v[174:175]
	v_pk_fma_f32 v[154:155], v[114:115], v[22:23], v[154:155]
	v_pk_fma_f32 v[156:157], v[112:113], v[22:23], v[156:157]
	v_pk_fma_f32 v[158:159], v[110:111], v[22:23], v[158:159]
	v_pk_fma_f32 v[160:161], v[108:109], v[22:23], v[160:161]
	v_pk_fma_f32 v[162:163], v[106:107], v[22:23], v[162:163]
	v_pk_fma_f32 v[164:165], v[104:105], v[22:23], v[164:165]
	v_pk_fma_f32 v[166:167], v[102:103], v[22:23], v[166:167]
	v_pk_fma_f32 v[168:169], v[100:101], v[22:23], v[168:169]
	v_pk_fma_f32 v[170:171], v[98:99], v[22:23], v[170:171]
	v_pk_fma_f32 v[172:173], v[96:97], v[22:23], v[172:173]
	v_pk_fma_f32 v[174:175], v[94:95], v[22:23], v[174:175]
	v_pk_fma_f32 v[176:177], v[92:93], v[22:23], v[176:177]
	v_pk_fma_f32 v[154:155], v[116:117], v[24:25], v[154:155]
	v_pk_fma_f32 v[156:157], v[114:115], v[24:25], v[156:157]
	v_pk_fma_f32 v[158:159], v[112:113], v[24:25], v[158:159]
	v_pk_fma_f32 v[160:161], v[110:111], v[24:25], v[160:161]
	v_pk_fma_f32 v[162:163], v[108:109], v[24:25], v[162:163]
	v_pk_fma_f32 v[164:165], v[106:107], v[24:25], v[164:165]
	v_pk_fma_f32 v[166:167], v[104:105], v[24:25], v[166:167]
	v_pk_fma_f32 v[168:169], v[102:103], v[24:25], v[168:169]
	v_pk_fma_f32 v[170:171], v[100:101], v[24:25], v[170:171]
	v_pk_fma_f32 v[172:173], v[98:99], v[24:25], v[172:173]
	v_pk_fma_f32 v[174:175], v[96:97], v[24:25], v[174:175]
	v_pk_fma_f32 v[176:177], v[94:95], v[24:25], v[176:177]
	v_pk_fma_f32 v[178:179], v[92:93], v[24:25], v[178:179]
	v_pk_fma_f32 v[154:155], v[118:119], v[26:27], v[154:155]
	v_pk_fma_f32 v[156:157], v[116:117], v[26:27], v[156:157]
	v_pk_fma_f32 v[158:159], v[114:115], v[26:27], v[158:159]
	v_pk_fma_f32 v[160:161], v[112:113], v[26:27], v[160:161]
	v_pk_fma_f32 v[162:163], v[110:111], v[26:27], v[162:163]
	v_pk_fma_f32 v[164:165], v[108:109], v[26:27], v[164:165]
	v_pk_fma_f32 v[166:167], v[106:107], v[26:27], v[166:167]
	v_pk_fma_f32 v[168:169], v[104:105], v[26:27], v[168:169]
	v_pk_fma_f32 v[170:171], v[102:103], v[26:27], v[170:171]
	v_pk_fma_f32 v[172:173], v[100:101], v[26:27], v[172:173]
	v_pk_fma_f32 v[174:175], v[98:99], v[26:27], v[174:175]
	v_pk_fma_f32 v[176:177], v[96:97], v[26:27], v[176:177]
	v_pk_fma_f32 v[178:179], v[94:95], v[26:27], v[178:179]
	v_pk_fma_f32 v[180:181], v[92:93], v[26:27], v[180:181]
	v_pk_fma_f32 v[154:155], v[120:121], v[28:29], v[154:155]
	v_pk_fma_f32 v[156:157], v[118:119], v[28:29], v[156:157]
	v_pk_fma_f32 v[158:159], v[116:117], v[28:29], v[158:159]
	v_pk_fma_f32 v[160:161], v[114:115], v[28:29], v[160:161]
	v_pk_fma_f32 v[162:163], v[112:113], v[28:29], v[162:163]
	v_pk_fma_f32 v[164:165], v[110:111], v[28:29], v[164:165]
	v_pk_fma_f32 v[166:167], v[108:109], v[28:29], v[166:167]
	v_pk_fma_f32 v[168:169], v[106:107], v[28:29], v[168:169]
	v_pk_fma_f32 v[170:171], v[104:105], v[28:29], v[170:171]
	v_pk_fma_f32 v[172:173], v[102:103], v[28:29], v[172:173]
	v_pk_fma_f32 v[174:175], v[100:101], v[28:29], v[174:175]
	v_pk_fma_f32 v[176:177], v[98:99], v[28:29], v[176:177]
	v_pk_fma_f32 v[178:179], v[96:97], v[28:29], v[178:179]
	v_pk_fma_f32 v[180:181], v[94:95], v[28:29], v[180:181]
	v_pk_fma_f32 v[182:183], v[92:93], v[28:29], v[182:183]
	v_pk_fma_f32 v[154:155], v[122:123], v[30:31], v[154:155]
	v_pk_fma_f32 v[156:157], v[120:121], v[30:31], v[156:157]
	v_pk_fma_f32 v[158:159], v[118:119], v[30:31], v[158:159]
	v_pk_fma_f32 v[160:161], v[116:117], v[30:31], v[160:161]
	v_pk_fma_f32 v[162:163], v[114:115], v[30:31], v[162:163]
	v_pk_fma_f32 v[164:165], v[112:113], v[30:31], v[164:165]
	v_pk_fma_f32 v[166:167], v[110:111], v[30:31], v[166:167]
	v_pk_fma_f32 v[168:169], v[108:109], v[30:31], v[168:169]
	v_pk_fma_f32 v[170:171], v[106:107], v[30:31], v[170:171]
	v_pk_fma_f32 v[172:173], v[104:105], v[30:31], v[172:173]
	v_pk_fma_f32 v[174:175], v[102:103], v[30:31], v[174:175]
	v_pk_fma_f32 v[176:177], v[100:101], v[30:31], v[176:177]
	v_pk_fma_f32 v[178:179], v[98:99], v[30:31], v[178:179]
	v_pk_fma_f32 v[180:181], v[96:97], v[30:31], v[180:181]
	v_pk_fma_f32 v[182:183], v[94:95], v[30:31], v[182:183]
	v_pk_fma_f32 v[184:185], v[92:93], v[30:31], v[184:185]
; #define LAS __attribute__((address_space(3)))
; __device__ __forceinline__ float bf_lo(unsigned u) { return __uint_as_float(u << 16); }
; __device__ __forceinline__ float bf_hi(unsigned u) { return __uint_as_float(u & 0xffff0000u); }
; template <int PH> ...
;     ...
;         for (int r = 0; r < 31; ++r) if (r < ntap + 15) {
;             const unsigned v = *(const LAS unsigned*)(lds + ((34 + 16 * PH + kb + r) & 63) * 2048 + tid * 4);
;             const f32x2 x = (f32x2){bf_lo(v), bf_hi(v)};
; #pragma unroll
;             for (int t = 0; t < 16; ++t) { const int k = r - t; if (k >= 0 && k < ntap) outv[t] = __builtin_elementwise_fma(w[k], x, outv[t]); }
	v_pk_fma_f32 v[154:155], v[124:125], v[32:33], v[154:155]
	v_pk_fma_f32 v[156:157], v[122:123], v[32:33], v[156:157]
	v_pk_fma_f32 v[158:159], v[120:121], v[32:33], v[158:159]
	v_pk_fma_f32 v[160:161], v[118:119], v[32:33], v[160:161]
	v_pk_fma_f32 v[162:163], v[116:117], v[32:33], v[162:163]
	v_pk_fma_f32 v[164:165], v[114:115], v[32:33], v[164:165]
	v_pk_fma_f32 v[166:167], v[112:113], v[32:33], v[166:167]
	v_pk_fma_f32 v[168:169], v[110:111], v[32:33], v[168:169]
	v_pk_fma_f32 v[170:171], v[108:109], v[32:33], v[170:171]
	v_pk_fma_f32 v[172:173], v[106:107], v[32:33], v[172:173]
	v_pk_fma_f32 v[174:175], v[104:105], v[32:33], v[174:175]
	v_pk_fma_f32 v[176:177], v[102:103], v[32:33], v[176:177]
	v_pk_fma_f32 v[178:179], v[100:101], v[32:33], v[178:179]
	v_pk_fma_f32 v[180:181], v[98:99], v[32:33], v[180:181]
	v_pk_fma_f32 v[182:183], v[96:97], v[32:33], v[182:183]
	v_pk_fma_f32 v[184:185], v[94:95], v[32:33], v[184:185]
	v_pk_fma_f32 v[154:155], v[126:127], v[34:35], v[154:155]
	v_pk_fma_f32 v[156:157], v[124:125], v[34:35], v[156:157]
	v_pk_fma_f32 v[158:159], v[122:123], v[34:35], v[158:159]
	v_pk_fma_f32 v[160:161], v[120:121], v[34:35], v[160:161]
	v_pk_fma_f32 v[162:163], v[118:119], v[34:35], v[162:163]
	v_pk_fma_f32 v[164:165], v[116:117], v[34:35], v[164:165]
	v_pk_fma_f32 v[166:167], v[114:115], v[34:35], v[166:167]
	v_pk_fma_f32 v[168:169], v[112:113], v[34:35], v[168:169]
	v_pk_fma_f32 v[170:171], v[110:111], v[34:35], v[170:171]
	v_pk_fma_f32 v[172:173], v[108:109], v[34:35], v[172:173]
	v_pk_fma_f32 v[174:175], v[106:107], v[34:35], v[174:175]
	v_pk_fma_f32 v[176:177], v[104:105], v[34:35], v[176:177]
	v_pk_fma_f32 v[178:179], v[102:103], v[34:35], v[178:179]
	v_pk_fma_f32 v[180:181], v[100:101], v[34:35], v[180:181]
	v_pk_fma_f32 v[182:183], v[98:99], v[34:35], v[182:183]
	v_pk_fma_f32 v[184:185], v[96:97], v[34:35], v[184:185]
	v_pk_fma_f32 v[154:155], v[128:129], v[36:37], v[154:155]
	v_pk_fma_f32 v[156:157], v[126:127], v[36:37], v[156:157]
	v_pk_fma_f32 v[158:159], v[124:125], v[36:37], v[158:159]
	v_pk_fma_f32 v[160:161], v[122:123], v[36:37], v[160:161]
	v_pk_fma_f32 v[162:163], v[120:121], v[36:37], v[162:163]
	v_pk_fma_f32 v[164:165], v[118:119], v[36:37], v[164:165]
	v_pk_fma_f32 v[166:167], v[116:117], v[36:37], v[166:167]
	v_pk_fma_f32 v[168:169], v[114:115], v[36:37], v[168:169]
	v_pk_fma_f32 v[170:171], v[112:113], v[36:37], v[170:171]
	v_pk_fma_f32 v[172:173], v[110:111], v[36:37], v[172:173]
	v_pk_fma_f32 v[174:175], v[108:109], v[36:37], v[174:175]
	v_pk_fma_f32 v[176:177], v[106:107], v[36:37], v[176:177]
	v_pk_fma_f32 v[178:179], v[104:105], v[36:37], v[178:179]
	v_pk_fma_f32 v[180:181], v[102:103], v[36:37], v[180:181]
	v_pk_fma_f32 v[182:183], v[100:101], v[36:37], v[182:183]
	v_pk_fma_f32 v[184:185], v[98:99], v[36:37], v[184:185]
	v_pk_fma_f32 v[154:155], v[130:131], v[38:39], v[154:155]
	v_pk_fma_f32 v[156:157], v[128:129], v[38:39], v[156:157]
	v_pk_fma_f32 v[158:159], v[126:127], v[38:39], v[158:159]
	v_pk_fma_f32 v[160:161], v[124:125], v[38:39], v[160:161]
	v_pk_fma_f32 v[162:163], v[122:123], v[38:39], v[162:163]
	v_pk_fma_f32 v[164:165], v[120:121], v[38:39], v[164:165]
	v_pk_fma_f32 v[166:167], v[118:119], v[38:39], v[166:167]
	v_pk_fma_f32 v[168:169], v[116:117], v[38:39], v[168:169]
	v_pk_fma_f32 v[170:171], v[114:115], v[38:39], v[170:171]
	v_pk_fma_f32 v[172:173], v[112:113], v[38:39], v[172:173]
	v_pk_fma_f32 v[174:175], v[110:111], v[38:39], v[174:175]
	v_pk_fma_f32 v[176:177], v[108:109], v[38:39], v[176:177]
	v_pk_fma_f32 v[178:179], v[106:107], v[38:39], v[178:179]
	v_pk_fma_f32 v[180:181], v[104:105], v[38:39], v[180:181]
	v_pk_fma_f32 v[182:183], v[102:103], v[38:39], v[182:183]
	v_pk_fma_f32 v[184:185], v[100:101], v[38:39], v[184:185]
	v_pk_fma_f32 v[154:155], v[132:133], v[40:41], v[154:155]
	v_pk_fma_f32 v[156:157], v[130:131], v[40:41], v[156:157]
	v_pk_fma_f32 v[158:159], v[128:129], v[40:41], v[158:159]
	v_pk_fma_f32 v[160:161], v[126:127], v[40:41], v[160:161]
	v_pk_fma_f32 v[162:163], v[124:125], v[40:41], v[162:163]
	v_pk_fma_f32 v[164:165], v[122:123], v[40:41], v[164:165]
	v_pk_fma_f32 v[166:167], v[120:121], v[40:41], v[166:167]
	v_pk_fma_f32 v[168:169], v[118:119], v[40:41], v[168:169]
	v_pk_fma_f32 v[170:171], v[116:117], v[40:41], v[170:171]
	v_pk_fma_f32 v[172:173], v[114:115], v[40:41], v[172:173]
	v_pk_fma_f32 v[174:175], v[112:113], v[40:41], v[174:175]
	v_pk_fma_f32 v[176:177], v[110:111], v[40:41], v[176:177]
	v_pk_fma_f32 v[178:179], v[108:109], v[40:41], v[178:179]
	v_pk_fma_f32 v[180:181], v[106:107], v[40:41], v[180:181]
	v_pk_fma_f32 v[182:183], v[104:105], v[40:41], v[182:183]
	v_pk_fma_f32 v[184:185], v[102:103], v[40:41], v[184:185]
	v_pk_fma_f32 v[154:155], v[134:135], v[42:43], v[154:155]
	v_pk_fma_f32 v[156:157], v[132:133], v[42:43], v[156:157]
	v_pk_fma_f32 v[158:159], v[130:131], v[42:43], v[158:159]
	v_pk_fma_f32 v[160:161], v[128:129], v[42:43], v[160:161]
	v_pk_fma_f32 v[162:163], v[126:127], v[42:43], v[162:163]
	v_pk_fma_f32 v[164:165], v[124:125], v[42:43], v[164:165]
	v_pk_fma_f32 v[166:167], v[122:123], v[42:43], v[166:167]
	v_pk_fma_f32 v[168:169], v[120:121], v[42:43], v[168:169]
	v_pk_fma_f32 v[170:171], v[118:119], v[42:43], v[170:171]
	v_pk_fma_f32 v[172:173], v[116:117], v[42:43], v[172:173]
	v_pk_fma_f32 v[174:175], v[114:115], v[42:43], v[174:175]
	v_pk_fma_f32 v[176:177], v[112:113], v[42:43], v[176:177]
	v_pk_fma_f32 v[178:179], v[110:111], v[42:43], v[178:179]
	v_pk_fma_f32 v[180:181], v[108:109], v[42:43], v[180:181]
	v_pk_fma_f32 v[182:183], v[106:107], v[42:43], v[182:183]
	v_pk_fma_f32 v[184:185], v[104:105], v[42:43], v[184:185]
; #define LAS __attribute__((address_space(3)))
; __device__ __forceinline__ float bf_lo(unsigned u) { return __uint_as_float(u << 16); }
; __device__ __forceinline__ float bf_hi(unsigned u) { return __uint_as_float(u & 0xffff0000u); }
; template <int PH> ...
;     ...
;         for (int r = 0; r < 31; ++r) if (r < ntap + 15) {
;             const unsigned v = *(const LAS unsigned*)(lds + ((34 + 16 * PH + kb + r) & 63) * 2048 + tid * 4);
;             const f32x2 x = (f32x2){bf_lo(v), bf_hi(v)};
; #pragma unroll
;             for (int t = 0; t < 16; ++t) { const int k = r - t; if (k >= 0 && k < ntap) outv[t] = __builtin_elementwise_fma(w[k], x, outv[t]); }
	v_pk_fma_f32 v[154:155], v[136:137], v[44:45], v[154:155]
	v_pk_fma_f32 v[156:157], v[134:135], v[44:45], v[156:157]
	v_pk_fma_f32 v[158:159], v[132:133], v[44:45], v[158:159]
	v_pk_fma_f32 v[160:161], v[130:131], v[44:45], v[160:161]
	v_pk_fma_f32 v[162:163], v[128:129], v[44:45], v[162:163]
	v_pk_fma_f32 v[164:165], v[126:127], v[44:45], v[164:165]
	v_pk_fma_f32 v[166:167], v[124:125], v[44:45], v[166:167]
	v_pk_fma_f32 v[168:169], v[122:123], v[44:45], v[168:169]
	v_pk_fma_f32 v[170:171], v[120:121], v[44:45], v[170:171]
	v_pk_fma_f32 v[172:173], v[118:119], v[44:45], v[172:173]
	v_pk_fma_f32 v[174:175], v[116:117], v[44:45], v[174:175]
	v_pk_fma_f32 v[176:177], v[114:115], v[44:45], v[176:177]
	v_pk_fma_f32 v[178:179], v[112:113], v[44:45], v[178:179]
	v_pk_fma_f32 v[180:181], v[110:111], v[44:45], v[180:181]
	v_pk_fma_f32 v[182:183], v[108:109], v[44:45], v[182:183]
	v_pk_fma_f32 v[184:185], v[106:107], v[44:45], v[184:185]
	v_pk_fma_f32 v[154:155], v[138:139], v[46:47], v[154:155]
	v_pk_fma_f32 v[156:157], v[136:137], v[46:47], v[156:157]
	v_pk_fma_f32 v[158:159], v[134:135], v[46:47], v[158:159]
	v_pk_fma_f32 v[160:161], v[132:133], v[46:47], v[160:161]
	v_pk_fma_f32 v[162:163], v[130:131], v[46:47], v[162:163]
	v_pk_fma_f32 v[164:165], v[128:129], v[46:47], v[164:165]
	v_pk_fma_f32 v[166:167], v[126:127], v[46:47], v[166:167]
	v_pk_fma_f32 v[168:169], v[124:125], v[46:47], v[168:169]
	v_pk_fma_f32 v[170:171], v[122:123], v[46:47], v[170:171]
	v_pk_fma_f32 v[172:173], v[120:121], v[46:47], v[172:173]
	v_pk_fma_f32 v[174:175], v[118:119], v[46:47], v[174:175]
	v_pk_fma_f32 v[176:177], v[116:117], v[46:47], v[176:177]
	v_pk_fma_f32 v[178:179], v[114:115], v[46:47], v[178:179]
	v_pk_fma_f32 v[180:181], v[112:113], v[46:47], v[180:181]
	v_pk_fma_f32 v[182:183], v[110:111], v[46:47], v[182:183]
	v_pk_fma_f32 v[184:185], v[108:109], v[46:47], v[184:185]
	v_pk_fma_f32 v[154:155], v[140:141], v[48:49], v[154:155]
	v_pk_fma_f32 v[156:157], v[138:139], v[48:49], v[156:157]
	v_pk_fma_f32 v[158:159], v[136:137], v[48:49], v[158:159]
	v_pk_fma_f32 v[160:161], v[134:135], v[48:49], v[160:161]
	v_pk_fma_f32 v[162:163], v[132:133], v[48:49], v[162:163]
	v_pk_fma_f32 v[164:165], v[130:131], v[48:49], v[164:165]
	v_pk_fma_f32 v[166:167], v[128:129], v[48:49], v[166:167]
	v_pk_fma_f32 v[168:169], v[126:127], v[48:49], v[168:169]
	v_pk_fma_f32 v[170:171], v[124:125], v[48:49], v[170:171]
	v_pk_fma_f32 v[172:173], v[122:123], v[48:49], v[172:173]
	v_pk_fma_f32 v[174:175], v[120:121], v[48:49], v[174:175]
	v_pk_fma_f32 v[176:177], v[118:119], v[48:49], v[176:177]
	v_pk_fma_f32 v[178:179], v[116:117], v[48:49], v[178:179]
	v_pk_fma_f32 v[180:181], v[114:115], v[48:49], v[180:181]
	v_pk_fma_f32 v[182:183], v[112:113], v[48:49], v[182:183]
	v_pk_fma_f32 v[184:185], v[110:111], v[48:49], v[184:185]
	v_pk_fma_f32 v[154:155], v[142:143], v[50:51], v[154:155]
	v_pk_fma_f32 v[156:157], v[140:141], v[50:51], v[156:157]
	v_pk_fma_f32 v[158:159], v[138:139], v[50:51], v[158:159]
	v_pk_fma_f32 v[160:161], v[136:137], v[50:51], v[160:161]
	v_pk_fma_f32 v[162:163], v[134:135], v[50:51], v[162:163]
	v_pk_fma_f32 v[164:165], v[132:133], v[50:51], v[164:165]
	v_pk_fma_f32 v[166:167], v[130:131], v[50:51], v[166:167]
	v_pk_fma_f32 v[168:169], v[128:129], v[50:51], v[168:169]
	v_pk_fma_f32 v[170:171], v[126:127], v[50:51], v[170:171]
	v_pk_fma_f32 v[172:173], v[124:125], v[50:51], v[172:173]
	v_pk_fma_f32 v[174:175], v[122:123], v[50:51], v[174:175]
	v_pk_fma_f32 v[176:177], v[120:121], v[50:51], v[176:177]
	v_pk_fma_f32 v[178:179], v[118:119], v[50:51], v[178:179]
	v_pk_fma_f32 v[180:181], v[116:117], v[50:51], v[180:181]
	v_pk_fma_f32 v[182:183], v[114:115], v[50:51], v[182:183]
	v_pk_fma_f32 v[184:185], v[112:113], v[50:51], v[184:185]
	v_pk_fma_f32 v[154:155], v[144:145], v[52:53], v[154:155]
	v_pk_fma_f32 v[156:157], v[142:143], v[52:53], v[156:157]
	v_pk_fma_f32 v[158:159], v[140:141], v[52:53], v[158:159]
	v_pk_fma_f32 v[160:161], v[138:139], v[52:53], v[160:161]
	v_pk_fma_f32 v[162:163], v[136:137], v[52:53], v[162:163]
	v_pk_fma_f32 v[164:165], v[134:135], v[52:53], v[164:165]
	v_pk_fma_f32 v[166:167], v[132:133], v[52:53], v[166:167]
	v_pk_fma_f32 v[168:169], v[130:131], v[52:53], v[168:169]
	v_pk_fma_f32 v[170:171], v[128:129], v[52:53], v[170:171]
	v_pk_fma_f32 v[172:173], v[126:127], v[52:53], v[172:173]
	v_pk_fma_f32 v[174:175], v[124:125], v[52:53], v[174:175]
	v_pk_fma_f32 v[176:177], v[122:123], v[52:53], v[176:177]
	v_pk_fma_f32 v[178:179], v[120:121], v[52:53], v[178:179]
	v_pk_fma_f32 v[180:181], v[118:119], v[52:53], v[180:181]
	v_pk_fma_f32 v[182:183], v[116:117], v[52:53], v[182:183]
	v_pk_fma_f32 v[184:185], v[114:115], v[52:53], v[184:185]
	v_pk_fma_f32 v[154:155], v[146:147], v[54:55], v[154:155]
	v_pk_fma_f32 v[156:157], v[144:145], v[54:55], v[156:157]
	v_pk_fma_f32 v[158:159], v[142:143], v[54:55], v[158:159]
	v_pk_fma_f32 v[160:161], v[140:141], v[54:55], v[160:161]
	v_pk_fma_f32 v[162:163], v[138:139], v[54:55], v[162:163]
	v_pk_fma_f32 v[164:165], v[136:137], v[54:55], v[164:165]
	v_pk_fma_f32 v[166:167], v[134:135], v[54:55], v[166:167]
	v_pk_fma_f32 v[168:169], v[132:133], v[54:55], v[168:169]
	v_pk_fma_f32 v[170:171], v[130:131], v[54:55], v[170:171]
	v_pk_fma_f32 v[172:173], v[128:129], v[54:55], v[172:173]
	v_pk_fma_f32 v[174:175], v[126:127], v[54:55], v[174:175]
	v_pk_fma_f32 v[176:177], v[124:125], v[54:55], v[176:177]
	v_pk_fma_f32 v[178:179], v[122:123], v[54:55], v[178:179]
	v_pk_fma_f32 v[180:181], v[120:121], v[54:55], v[180:181]
	v_pk_fma_f32 v[182:183], v[118:119], v[54:55], v[182:183]
	v_pk_fma_f32 v[184:185], v[116:117], v[54:55], v[184:185]
; #define LAS __attribute__((address_space(3)))
; __device__ __forceinline__ float bf_lo(unsigned u) { return __uint_as_float(u << 16); }
; __device__ __forceinline__ float bf_hi(unsigned u) { return __uint_as_float(u & 0xffff0000u); }
; template <int PH> ...
;     ...
;         for (int r = 0; r < 31; ++r) if (r < ntap + 15) {
;             const unsigned v = *(const LAS unsigned*)(lds + ((34 + 16 * PH + kb + r) & 63) * 2048 + tid * 4);
;             const f32x2 x = (f32x2){bf_lo(v), bf_hi(v)};
; #pragma unroll
;             for (int t = 0; t < 16; ++t) { const int k = r - t; if (k >= 0 && k < ntap) outv[t] = __builtin_elementwise_fma(w[k], x, outv[t]); }
	v_pk_fma_f32 v[154:155], v[148:149], v[56:57], v[154:155]
	v_pk_fma_f32 v[156:157], v[146:147], v[56:57], v[156:157]
	v_pk_fma_f32 v[158:159], v[144:145], v[56:57], v[158:159]
	v_pk_fma_f32 v[160:161], v[142:143], v[56:57], v[160:161]
	v_pk_fma_f32 v[162:163], v[140:141], v[56:57], v[162:163]
	v_pk_fma_f32 v[164:165], v[138:139], v[56:57], v[164:165]
	v_pk_fma_f32 v[166:167], v[136:137], v[56:57], v[166:167]
	v_pk_fma_f32 v[168:169], v[134:135], v[56:57], v[168:169]
	v_pk_fma_f32 v[170:171], v[132:133], v[56:57], v[170:171]
	v_pk_fma_f32 v[172:173], v[130:131], v[56:57], v[172:173]
	v_pk_fma_f32 v[174:175], v[128:129], v[56:57], v[174:175]
	v_pk_fma_f32 v[176:177], v[126:127], v[56:57], v[176:177]
	v_pk_fma_f32 v[178:179], v[124:125], v[56:57], v[178:179]
	v_pk_fma_f32 v[180:181], v[122:123], v[56:57], v[180:181]
	v_pk_fma_f32 v[182:183], v[120:121], v[56:57], v[182:183]
	v_pk_fma_f32 v[184:185], v[118:119], v[56:57], v[184:185]
	v_pk_fma_f32 v[154:155], v[150:151], v[58:59], v[154:155]
	v_pk_fma_f32 v[156:157], v[148:149], v[58:59], v[156:157]
	v_pk_fma_f32 v[158:159], v[146:147], v[58:59], v[158:159]
	v_pk_fma_f32 v[160:161], v[144:145], v[58:59], v[160:161]
	v_pk_fma_f32 v[162:163], v[142:143], v[58:59], v[162:163]
	v_pk_fma_f32 v[164:165], v[140:141], v[58:59], v[164:165]
	v_pk_fma_f32 v[166:167], v[138:139], v[58:59], v[166:167]
	v_pk_fma_f32 v[168:169], v[136:137], v[58:59], v[168:169]
	v_pk_fma_f32 v[170:171], v[134:135], v[58:59], v[170:171]
	v_pk_fma_f32 v[172:173], v[132:133], v[58:59], v[172:173]
	v_pk_fma_f32 v[174:175], v[130:131], v[58:59], v[174:175]
	v_pk_fma_f32 v[176:177], v[128:129], v[58:59], v[176:177]
	v_pk_fma_f32 v[178:179], v[126:127], v[58:59], v[178:179]
	v_pk_fma_f32 v[180:181], v[124:125], v[58:59], v[180:181]
	v_pk_fma_f32 v[182:183], v[122:123], v[58:59], v[182:183]
	v_pk_fma_f32 v[184:185], v[120:121], v[58:59], v[184:185]
	v_pk_fma_f32 v[154:155], v[152:153], v[60:61], v[154:155]
	v_pk_fma_f32 v[156:157], v[150:151], v[60:61], v[156:157]
	v_pk_fma_f32 v[158:159], v[148:149], v[60:61], v[158:159]
	v_pk_fma_f32 v[160:161], v[146:147], v[60:61], v[160:161]
	v_pk_fma_f32 v[162:163], v[144:145], v[60:61], v[162:163]
	v_pk_fma_f32 v[164:165], v[142:143], v[60:61], v[164:165]
	v_pk_fma_f32 v[166:167], v[140:141], v[60:61], v[166:167]
	v_pk_fma_f32 v[168:169], v[138:139], v[60:61], v[168:169]
	v_pk_fma_f32 v[170:171], v[136:137], v[60:61], v[170:171]
	v_pk_fma_f32 v[172:173], v[134:135], v[60:61], v[172:173]
	v_pk_fma_f32 v[174:175], v[132:133], v[60:61], v[174:175]
	v_pk_fma_f32 v[176:177], v[130:131], v[60:61], v[176:177]
	v_pk_fma_f32 v[178:179], v[128:129], v[60:61], v[178:179]
	v_pk_fma_f32 v[180:181], v[126:127], v[60:61], v[180:181]
	v_pk_fma_f32 v[182:183], v[124:125], v[60:61], v[182:183]
	v_pk_fma_f32 v[184:185], v[122:123], v[60:61], v[184:185]
	v_pk_fma_f32 v[156:157], v[152:153], v[62:63], v[156:157]
	v_pk_fma_f32 v[158:159], v[150:151], v[62:63], v[158:159]
	v_pk_fma_f32 v[160:161], v[148:149], v[62:63], v[160:161]
	v_pk_fma_f32 v[162:163], v[146:147], v[62:63], v[162:163]
	v_pk_fma_f32 v[164:165], v[144:145], v[62:63], v[164:165]
	v_pk_fma_f32 v[166:167], v[142:143], v[62:63], v[166:167]
	v_pk_fma_f32 v[168:169], v[140:141], v[62:63], v[168:169]
	v_pk_fma_f32 v[170:171], v[138:139], v[62:63], v[170:171]
	v_pk_fma_f32 v[172:173], v[136:137], v[62:63], v[172:173]
	v_pk_fma_f32 v[174:175], v[134:135], v[62:63], v[174:175]
	v_pk_fma_f32 v[176:177], v[132:133], v[62:63], v[176:177]
	v_pk_fma_f32 v[178:179], v[130:131], v[62:63], v[178:179]
	v_pk_fma_f32 v[180:181], v[128:129], v[62:63], v[180:181]
	v_pk_fma_f32 v[182:183], v[126:127], v[62:63], v[182:183]
	v_pk_fma_f32 v[184:185], v[124:125], v[62:63], v[184:185]
	v_pk_fma_f32 v[158:159], v[152:153], v[64:65], v[158:159]
	v_pk_fma_f32 v[160:161], v[150:151], v[64:65], v[160:161]
	v_pk_fma_f32 v[162:163], v[148:149], v[64:65], v[162:163]
	v_pk_fma_f32 v[164:165], v[146:147], v[64:65], v[164:165]
	v_pk_fma_f32 v[166:167], v[144:145], v[64:65], v[166:167]
	v_pk_fma_f32 v[168:169], v[142:143], v[64:65], v[168:169]
	v_pk_fma_f32 v[170:171], v[140:141], v[64:65], v[170:171]
	v_pk_fma_f32 v[172:173], v[138:139], v[64:65], v[172:173]
	v_pk_fma_f32 v[174:175], v[136:137], v[64:65], v[174:175]
	v_pk_fma_f32 v[176:177], v[134:135], v[64:65], v[176:177]
	v_pk_fma_f32 v[178:179], v[132:133], v[64:65], v[178:179]
	v_pk_fma_f32 v[180:181], v[130:131], v[64:65], v[180:181]
	v_pk_fma_f32 v[182:183], v[128:129], v[64:65], v[182:183]
	v_pk_fma_f32 v[184:185], v[126:127], v[64:65], v[184:185]
	v_pk_fma_f32 v[160:161], v[152:153], v[66:67], v[160:161]
	v_pk_fma_f32 v[162:163], v[150:151], v[66:67], v[162:163]
	v_pk_fma_f32 v[164:165], v[148:149], v[66:67], v[164:165]
	v_pk_fma_f32 v[166:167], v[146:147], v[66:67], v[166:167]
	v_pk_fma_f32 v[168:169], v[144:145], v[66:67], v[168:169]
	v_pk_fma_f32 v[170:171], v[142:143], v[66:67], v[170:171]
	v_pk_fma_f32 v[172:173], v[140:141], v[66:67], v[172:173]
	v_pk_fma_f32 v[174:175], v[138:139], v[66:67], v[174:175]
	v_pk_fma_f32 v[176:177], v[136:137], v[66:67], v[176:177]
	v_pk_fma_f32 v[178:179], v[134:135], v[66:67], v[178:179]
	v_pk_fma_f32 v[180:181], v[132:133], v[66:67], v[180:181]
	v_pk_fma_f32 v[182:183], v[130:131], v[66:67], v[182:183]
	v_pk_fma_f32 v[184:185], v[128:129], v[66:67], v[184:185]
	v_pk_fma_f32 v[162:163], v[152:153], v[68:69], v[162:163]
	v_pk_fma_f32 v[164:165], v[150:151], v[68:69], v[164:165]
	v_pk_fma_f32 v[166:167], v[148:149], v[68:69], v[166:167]
	v_pk_fma_f32 v[168:169], v[146:147], v[68:69], v[168:169]
	v_pk_fma_f32 v[170:171], v[144:145], v[68:69], v[170:171]
	v_pk_fma_f32 v[172:173], v[142:143], v[68:69], v[172:173]
; #define LAS __attribute__((address_space(3)))
; template <int PH> ...
;     ...
;             for (int t = 0; t < 16; ++t) { const int k = r - t; if (k >= 0 && k < ntap) outv[t] = __builtin_elementwise_fma(w[k], x, outv[t]); }
;     ...
;     {
;         float s[16], q[16];
; #pragma unroll
;         for (int t = 0; t < 16; ++t) { s[t] = outv[t][0] + outv[t][1]; q[t] = outv[t][0] * outv[t][0] + outv[t][1] * outv[t][1]; }
; #pragma unroll
;         for (int lvl = 0; lvl < 4; ++lvl) {
;             const int half = 8 >> lvl, off = 32 >> lvl; const bool hi = (lane & off) != 0;
; #pragma unroll
;             for (int i = 0; i < half; ++i) {
;                 const float ks = hi ? s[i + half] : s[i], ss = hi ? s[i] : s[i + half]; s[i] = ks + __shfl_xor(ss, off);
;                 const float kq = hi ? q[i + half] : q[i], sq = hi ? q[i] : q[i + half]; q[i] = kq + __shfl_xor(sq, off);
;             }
;         }
;         s[0] += __shfl_xor(s[0], 2); q[0] += __shfl_xor(q[0], 2);
;         s[0] += __shfl_xor(s[0], 1); q[0] += __shfl_xor(q[0], 1);
;         if ((lane & 3) == 0) *(LAS f32x2*)(red + ((lane >> 2) * 8 + wid) * 2) = (f32x2){s[0], q[0]};
	v_pk_fma_f32 v[174:175], v[140:141], v[68:69], v[174:175]
	v_pk_fma_f32 v[176:177], v[138:139], v[68:69], v[176:177]
	v_pk_fma_f32 v[178:179], v[136:137], v[68:69], v[178:179]
	v_pk_fma_f32 v[180:181], v[134:135], v[68:69], v[180:181]
	v_pk_fma_f32 v[182:183], v[132:133], v[68:69], v[182:183]
	v_pk_fma_f32 v[184:185], v[130:131], v[68:69], v[184:185]
	v_pk_fma_f32 v[164:165], v[152:153], v[70:71], v[164:165]
	v_pk_fma_f32 v[166:167], v[150:151], v[70:71], v[166:167]
	v_pk_fma_f32 v[168:169], v[148:149], v[70:71], v[168:169]
	v_pk_fma_f32 v[170:171], v[146:147], v[70:71], v[170:171]
	v_pk_fma_f32 v[172:173], v[144:145], v[70:71], v[172:173]
	v_pk_fma_f32 v[174:175], v[142:143], v[70:71], v[174:175]
	v_pk_fma_f32 v[176:177], v[140:141], v[70:71], v[176:177]
	v_pk_fma_f32 v[178:179], v[138:139], v[70:71], v[178:179]
	v_pk_fma_f32 v[180:181], v[136:137], v[70:71], v[180:181]
	v_pk_fma_f32 v[182:183], v[134:135], v[70:71], v[182:183]
	v_pk_fma_f32 v[184:185], v[132:133], v[70:71], v[184:185]
	v_pk_fma_f32 v[166:167], v[152:153], v[72:73], v[166:167]
	v_pk_fma_f32 v[168:169], v[150:151], v[72:73], v[168:169]
	v_pk_fma_f32 v[170:171], v[148:149], v[72:73], v[170:171]
	v_pk_fma_f32 v[172:173], v[146:147], v[72:73], v[172:173]
	v_pk_fma_f32 v[174:175], v[144:145], v[72:73], v[174:175]
	v_pk_fma_f32 v[176:177], v[142:143], v[72:73], v[176:177]
	v_pk_fma_f32 v[178:179], v[140:141], v[72:73], v[178:179]
	v_pk_fma_f32 v[180:181], v[138:139], v[72:73], v[180:181]
	v_pk_fma_f32 v[182:183], v[136:137], v[72:73], v[182:183]
	v_pk_fma_f32 v[184:185], v[134:135], v[72:73], v[184:185]
	v_pk_fma_f32 v[168:169], v[152:153], v[74:75], v[168:169]
	v_pk_fma_f32 v[170:171], v[150:151], v[74:75], v[170:171]
	v_pk_fma_f32 v[172:173], v[148:149], v[74:75], v[172:173]
	v_pk_fma_f32 v[174:175], v[146:147], v[74:75], v[174:175]
	v_pk_fma_f32 v[176:177], v[144:145], v[74:75], v[176:177]
	v_pk_fma_f32 v[178:179], v[142:143], v[74:75], v[178:179]
	v_pk_fma_f32 v[180:181], v[140:141], v[74:75], v[180:181]
	v_pk_fma_f32 v[182:183], v[138:139], v[74:75], v[182:183]
	v_pk_fma_f32 v[184:185], v[136:137], v[74:75], v[184:185]
	v_pk_fma_f32 v[170:171], v[152:153], v[76:77], v[170:171]
	v_pk_fma_f32 v[172:173], v[150:151], v[76:77], v[172:173]
	v_pk_fma_f32 v[174:175], v[148:149], v[76:77], v[174:175]
	v_pk_fma_f32 v[176:177], v[146:147], v[76:77], v[176:177]
	v_pk_fma_f32 v[178:179], v[144:145], v[76:77], v[178:179]
	v_pk_fma_f32 v[180:181], v[142:143], v[76:77], v[180:181]
	v_pk_fma_f32 v[182:183], v[140:141], v[76:77], v[182:183]
	v_pk_fma_f32 v[184:185], v[138:139], v[76:77], v[184:185]
	v_pk_fma_f32 v[172:173], v[152:153], v[78:79], v[172:173]
	v_pk_fma_f32 v[174:175], v[150:151], v[78:79], v[174:175]
	v_pk_fma_f32 v[176:177], v[148:149], v[78:79], v[176:177]
	v_pk_fma_f32 v[178:179], v[146:147], v[78:79], v[178:179]
	v_pk_fma_f32 v[180:181], v[144:145], v[78:79], v[180:181]
	v_pk_fma_f32 v[182:183], v[142:143], v[78:79], v[182:183]
	v_pk_fma_f32 v[184:185], v[140:141], v[78:79], v[184:185]
	v_pk_fma_f32 v[174:175], v[152:153], v[80:81], v[174:175]
	v_pk_fma_f32 v[176:177], v[150:151], v[80:81], v[176:177]
	v_pk_fma_f32 v[178:179], v[148:149], v[80:81], v[178:179]
	v_pk_fma_f32 v[180:181], v[146:147], v[80:81], v[180:181]
	v_pk_fma_f32 v[182:183], v[144:145], v[80:81], v[182:183]
	v_pk_fma_f32 v[184:185], v[142:143], v[80:81], v[184:185]
	v_pk_fma_f32 v[176:177], v[152:153], v[82:83], v[176:177]
	v_pk_fma_f32 v[178:179], v[150:151], v[82:83], v[178:179]
	v_pk_fma_f32 v[180:181], v[148:149], v[82:83], v[180:181]
	v_pk_fma_f32 v[182:183], v[146:147], v[82:83], v[182:183]
	v_pk_fma_f32 v[184:185], v[144:145], v[82:83], v[184:185]
	v_pk_fma_f32 v[178:179], v[152:153], v[84:85], v[178:179]
	v_pk_fma_f32 v[180:181], v[150:151], v[84:85], v[180:181]
	v_pk_fma_f32 v[182:183], v[148:149], v[84:85], v[182:183]
	v_pk_fma_f32 v[184:185], v[146:147], v[84:85], v[184:185]
	v_pk_fma_f32 v[180:181], v[152:153], v[86:87], v[180:181]
	v_pk_fma_f32 v[182:183], v[150:151], v[86:87], v[182:183]
	v_pk_fma_f32 v[184:185], v[148:149], v[86:87], v[184:185]
	v_pk_fma_f32 v[182:183], v[152:153], v[88:89], v[182:183]
	v_pk_fma_f32 v[184:185], v[150:151], v[88:89], v[184:185]
	v_pk_fma_f32 v[184:185], v[152:153], v[90:91], v[184:185]
	s_mov_b32 s98, 0xffff0000
	s_mov_b32 s99, 0xffff0000
	v_xor_b32_e32 v246, 16, v224
	v_lshlrev_b32_e32 v246, 2, v246
	v_add_f32_e32 v228, v154, v155
	v_mul_f32_e32 v229, v154, v154
	v_add_f32_e32 v230, v156, v157
	v_mul_f32_e32 v231, v156, v156
	v_add_f32_e32 v232, v158, v159
	v_mul_f32_e32 v233, v158, v158
	v_add_f32_e32 v234, v160, v161
	v_mul_f32_e32 v235, v160, v160
	v_add_f32_e32 v236, v162, v163
	v_mul_f32_e32 v237, v162, v162
	v_add_f32_e32 v238, v164, v165
	v_mul_f32_e32 v239, v164, v164
	v_add_f32_e32 v240, v166, v167
	v_mul_f32_e32 v241, v166, v166
	v_add_f32_e32 v242, v168, v169
	v_mul_f32_e32 v243, v168, v168
	v_fmac_f32_e32 v229, v155, v155
	v_fmac_f32_e32 v231, v157, v157
	v_fmac_f32_e32 v233, v159, v159
	v_fmac_f32_e32 v235, v161, v161
	v_fmac_f32_e32 v237, v163, v163
	v_fmac_f32_e32 v239, v165, v165
	v_fmac_f32_e32 v241, v167, v167
	v_fmac_f32_e32 v243, v169, v169
	s_nop 1
	v_permlane32_swap_b32_e32 v228, v236
	v_permlane32_swap_b32_e32 v229, v237
	v_permlane32_swap_b32_e32 v230, v238
	v_permlane32_swap_b32_e32 v231, v239
	v_permlane32_swap_b32_e32 v232, v240
	v_permlane32_swap_b32_e32 v233, v241
	v_permlane32_swap_b32_e32 v234, v242
	v_permlane32_swap_b32_e32 v235, v243
	v_add_f32_e32 v228, v228, v236
	v_add_f32_e32 v229, v229, v237
	v_add_f32_e32 v230, v230, v238
	v_add_f32_e32 v231, v231, v239
	v_add_f32_e32 v232, v232, v240
	v_add_f32_e32 v233, v233, v241
	v_add_f32_e32 v234, v234, v242
	v_add_f32_e32 v235, v235, v243
	v_cndmask_b32_e64 v236, v232, v228, s[98:99]
	v_cndmask_b32_e64 v240, v228, v232, s[98:99]
	v_cndmask_b32_e64 v237, v233, v229, s[98:99]
	v_cndmask_b32_e64 v241, v229, v233, s[98:99]
	v_cndmask_b32_e64 v238, v234, v230, s[98:99]
	v_cndmask_b32_e64 v242, v230, v234, s[98:99]
	v_cndmask_b32_e64 v239, v235, v231, s[98:99]
	v_cndmask_b32_e64 v243, v231, v235, s[98:99]
	ds_bpermute_b32 v236, v246, v236
	ds_bpermute_b32 v237, v246, v237
	ds_bpermute_b32 v238, v246, v238
	ds_bpermute_b32 v239, v246, v239
	s_waitcnt lgkmcnt(0)
; #define LAS __attribute__((address_space(3)))
; template <int PH> ...
;     ...
;     {
;         float s[16], q[16];
; #pragma unroll
;         for (int t = 0; t < 16; ++t) { s[t] = outv[t][0] + outv[t][1]; q[t] = outv[t][0] * outv[t][0] + outv[t][1] * outv[t][1]; }
; #pragma unroll
;         for (int lvl = 0; lvl < 4; ++lvl) {
;             const int half = 8 >> lvl, off = 32 >> lvl; const bool hi = (lane & off) != 0;
; #pragma unroll
;             for (int i = 0; i < half; ++i) {
;                 const float ks = hi ? s[i + half] : s[i], ss = hi ? s[i] : s[i + half]; s[i] = ks + __shfl_xor(ss, off);
;                 const float kq = hi ? q[i + half] : q[i], sq = hi ? q[i] : q[i + half]; q[i] = kq + __shfl_xor(sq, off);
;             }
;         }
;         s[0] += __shfl_xor(s[0], 2); q[0] += __shfl_xor(q[0], 2);
;         s[0] += __shfl_xor(s[0], 1); q[0] += __shfl_xor(q[0], 1);
;         if ((lane & 3) == 0) *(LAS f32x2*)(red + ((lane >> 2) * 8 + wid) * 2) = (f32x2){s[0], q[0]};
;     }
;     __syncthreads();
;     if (has_next) {
; #pragma unroll
;         for (int q = 0; q < 4; ++q) { const int i = tid + q * 512; *(LAS u32x4*)(lds + ((34 + 16 * PH + 46 + (i >> 7)) & 63) * 2048 + (i & 127) * 16) = nx[q]; }
;     }
;     if (tid < 16) {
;         float S = 0.f, Q2 = 0.f;
; #pragma unroll
;         for (int wv = 0; wv < 8; ++wv) { const f32x2 t = *(const LAS f32x2*)(red + (tid * 8 + wv) * 2); S += t[0]; Q2 += t[1]; }
;         const float mean = S * (1.f / 1024.f), var = fmaxf(Q2 * (1.f / 1024.f) - mean * mean, 0.f);
;         *(LAS f32x2*)(stats + tid * 2) = (f32x2){mean, 1.0f / sqrtf(var + EPS)};
;     }
	v_add_f32_e32 v228, v240, v236
	v_add_f32_e32 v229, v241, v237
	v_add_f32_e32 v230, v242, v238
	v_add_f32_e32 v231, v243, v239
	v_add_f32_dpp v228, v228, v228 row_ror:8 row_mask:0xf bank_mask:0xf
	v_add_f32_dpp v229, v229, v229 row_ror:8 row_mask:0xf bank_mask:0xf
	v_add_f32_dpp v230, v230, v230 row_ror:8 row_mask:0xf bank_mask:0xf
	v_add_f32_dpp v231, v231, v231 row_ror:8 row_mask:0xf bank_mask:0xf
	v_add_f32_dpp v228, v228, v228 row_ror:4 row_mask:0xf bank_mask:0xf
	v_add_f32_dpp v229, v229, v229 row_ror:4 row_mask:0xf bank_mask:0xf
	v_add_f32_dpp v230, v230, v230 row_ror:4 row_mask:0xf bank_mask:0xf
	v_add_f32_dpp v231, v231, v231 row_ror:4 row_mask:0xf bank_mask:0xf
	v_add_f32_dpp v228, v228, v228 row_ror:2 row_mask:0xf bank_mask:0xf
	v_add_f32_dpp v229, v229, v229 row_ror:2 row_mask:0xf bank_mask:0xf
	v_add_f32_dpp v230, v230, v230 row_ror:2 row_mask:0xf bank_mask:0xf
	v_add_f32_dpp v231, v231, v231 row_ror:2 row_mask:0xf bank_mask:0xf
	v_add_f32_dpp v228, v228, v228 row_ror:1 row_mask:0xf bank_mask:0xf
	v_add_f32_dpp v229, v229, v229 row_ror:1 row_mask:0xf bank_mask:0xf
	v_add_f32_dpp v230, v230, v230 row_ror:1 row_mask:0xf bank_mask:0xf
	v_add_f32_dpp v231, v231, v231 row_ror:1 row_mask:0xf bank_mask:0xf
	s_mov_b64 s[30:31], exec
	s_mov_b32 s4, 0x00010001
	s_mov_b32 s5, 0x00010001
	s_mov_b64 exec, s[4:5]
	ds_write_b64 v253, v[228:229] offset:0
	ds_write_b64 v253, v[230:231] offset:64
	s_mov_b64 exec, s[30:31]
	v_add_f32_e32 v228, v170, v171
	v_mul_f32_e32 v229, v170, v170
	v_add_f32_e32 v230, v172, v173
	v_mul_f32_e32 v231, v172, v172
	v_add_f32_e32 v232, v174, v175
	v_mul_f32_e32 v233, v174, v174
	v_add_f32_e32 v234, v176, v177
	v_mul_f32_e32 v235, v176, v176
	v_add_f32_e32 v236, v178, v179
	v_mul_f32_e32 v237, v178, v178
	v_add_f32_e32 v238, v180, v181
	v_mul_f32_e32 v239, v180, v180
	v_add_f32_e32 v240, v182, v183
	v_mul_f32_e32 v241, v182, v182
	v_add_f32_e32 v242, v184, v185
	v_mul_f32_e32 v243, v184, v184
	v_fmac_f32_e32 v229, v171, v171
	v_fmac_f32_e32 v231, v173, v173
	v_fmac_f32_e32 v233, v175, v175
	v_fmac_f32_e32 v235, v177, v177
	v_fmac_f32_e32 v237, v179, v179
	v_fmac_f32_e32 v239, v181, v181
	v_fmac_f32_e32 v241, v183, v183
	v_fmac_f32_e32 v243, v185, v185
	s_nop 1
	v_permlane32_swap_b32_e32 v228, v236
	v_permlane32_swap_b32_e32 v229, v237
	v_permlane32_swap_b32_e32 v230, v238
	v_permlane32_swap_b32_e32 v231, v239
	v_permlane32_swap_b32_e32 v232, v240
	v_permlane32_swap_b32_e32 v233, v241
	v_permlane32_swap_b32_e32 v234, v242
	v_permlane32_swap_b32_e32 v235, v243
	v_add_f32_e32 v228, v228, v236
	v_add_f32_e32 v229, v229, v237
	v_add_f32_e32 v230, v230, v238
	v_add_f32_e32 v231, v231, v239
	v_add_f32_e32 v232, v232, v240
	v_add_f32_e32 v233, v233, v241
	v_add_f32_e32 v234, v234, v242
	v_add_f32_e32 v235, v235, v243
	v_cndmask_b32_e64 v236, v232, v228, s[98:99]
	v_cndmask_b32_e64 v240, v228, v232, s[98:99]
	v_cndmask_b32_e64 v237, v233, v229, s[98:99]
	v_cndmask_b32_e64 v241, v229, v233, s[98:99]
	v_cndmask_b32_e64 v238, v234, v230, s[98:99]
	v_cndmask_b32_e64 v242, v230, v234, s[98:99]
	v_cndmask_b32_e64 v239, v235, v231, s[98:99]
	v_cndmask_b32_e64 v243, v231, v235, s[98:99]
	ds_bpermute_b32 v236, v246, v236
	ds_bpermute_b32 v237, v246, v237
	ds_bpermute_b32 v238, v246, v238
	ds_bpermute_b32 v239, v246, v239
	s_waitcnt lgkmcnt(0)
	v_add_f32_e32 v228, v240, v236
	v_add_f32_e32 v229, v241, v237
	v_add_f32_e32 v230, v242, v238
	v_add_f32_e32 v231, v243, v239
	v_add_f32_dpp v228, v228, v228 row_ror:8 row_mask:0xf bank_mask:0xf
	v_add_f32_dpp v229, v229, v229 row_ror:8 row_mask:0xf bank_mask:0xf
	v_add_f32_dpp v230, v230, v230 row_ror:8 row_mask:0xf bank_mask:0xf
	v_add_f32_dpp v231, v231, v231 row_ror:8 row_mask:0xf bank_mask:0xf
	v_add_f32_dpp v228, v228, v228 row_ror:4 row_mask:0xf bank_mask:0xf
	v_add_f32_dpp v229, v229, v229 row_ror:4 row_mask:0xf bank_mask:0xf
	v_add_f32_dpp v230, v230, v230 row_ror:4 row_mask:0xf bank_mask:0xf
	v_add_f32_dpp v231, v231, v231 row_ror:4 row_mask:0xf bank_mask:0xf
	v_add_f32_dpp v228, v228, v228 row_ror:2 row_mask:0xf bank_mask:0xf
	v_add_f32_dpp v229, v229, v229 row_ror:2 row_mask:0xf bank_mask:0xf
	v_add_f32_dpp v230, v230, v230 row_ror:2 row_mask:0xf bank_mask:0xf
	v_add_f32_dpp v231, v231, v231 row_ror:2 row_mask:0xf bank_mask:0xf
	v_add_f32_dpp v228, v228, v228 row_ror:1 row_mask:0xf bank_mask:0xf
	v_add_f32_dpp v229, v229, v229 row_ror:1 row_mask:0xf bank_mask:0xf
	v_add_f32_dpp v230, v230, v230 row_ror:1 row_mask:0xf bank_mask:0xf
	v_add_f32_dpp v231, v231, v231 row_ror:1 row_mask:0xf bank_mask:0xf
	s_mov_b64 s[30:31], exec
	s_mov_b32 s4, 0x00010001
	s_mov_b32 s5, 0x00010001
	s_mov_b64 exec, s[4:5]
	ds_write_b64 v253, v[228:229] offset:512
	ds_write_b64 v253, v[230:231] offset:576
	s_mov_b64 exec, s[30:31]
	s_waitcnt lgkmcnt(0)
	s_barrier
	s_cmp_lg_u32 s87, 0
	s_cbranch_scc1 .Lc31_nostat
	s_mov_b64 s[30:31], exec
	s_mov_b64 exec, 0xffff
	v_lshlrev_b32_e32 v247, 6, v224
	ds_read_b128 v[228:231], v247 offset:0
	ds_read_b128 v[232:235], v247 offset:16
	ds_read_b128 v[236:239], v247 offset:32
	ds_read_b128 v[240:243], v247 offset:48
	s_waitcnt lgkmcnt(0)
	v_add_f32_e32 v228, v228, v230
	v_add_f32_e32 v229, v229, v231
	v_add_f32_e32 v232, v232, v234
	v_add_f32_e32 v233, v233, v235
	v_add_f32_e32 v236, v236, v238
	v_add_f32_e32 v237, v237, v239
	v_add_f32_e32 v240, v240, v242
	v_add_f32_e32 v241, v241, v243
	v_add_f32_e32 v228, v228, v232
	v_add_f32_e32 v229, v229, v233
	v_add_f32_e32 v236, v236, v240
	v_add_f32_e32 v237, v237, v241
	v_add_f32_e32 v228, v228, v236
	v_add_f32_e32 v229, v229, v237
	v_mul_f32_e32 v228, 0x3a800000, v228
	v_mul_f32_e32 v229, 0x3a800000, v229
	v_fma_f32 v229, -v228, v228, v229
	v_max_f32_e32 v229, 0, v229
	v_add_f32_e32 v229, 0x358637bd, v229
	v_rsq_f32_e32 v230, v229
	s_nop 0
	v_mul_f32_e32 v231, v229, v230
	v_mul_f32_e32 v231, v231, v230
	v_mov_b32_e32 v232, 0x3fc00000
	v_fma_f32 v231, v231, -0.5, v232
	v_mul_f32_e32 v229, v230, v231
	v_lshlrev_b32_e32 v247, 3, v224
	ds_write_b64 v247, v[228:229] offset:1024
	s_mov_b64 exec, s[30:31]
; #define LAS __attribute__((address_space(3)))
; __device__ __forceinline__ unsigned pk_bf16(float lo, float hi) { const f32x2 v = {lo, hi}; return __builtin_bit_cast(unsigned, __builtin_convertvector(v, bf16x2_t)); }
; __device__ __forceinline__ float bf_lo(unsigned u) { return __uint_as_float(u << 16); }
; __device__ __forceinline__ float bf_hi(unsigned u) { return __uint_as_float(u & 0xffff0000u); }
; __device__ __forceinline__ float siluf_(float x) { return x * sigmoidf_(x); }
; template <int PH> ...
;     ...
;     const f32x2 lg = *(const f32x2*)(lng + c2), lb = *(const f32x2*)(lnb + c2);
;     unsigned zz[16];
; #pragma unroll
;     for (int t = 0; t < 16; ++t) zz[t] = __builtin_nontemporal_load((const unsigned*)(SZB + (size_t)(t0 + t) * 1024 + c2));
; #pragma unroll
;     for (int t = 0; t < 16; ++t) {
;         const f32x2 st = *(const LAS f32x2*)(stats + t * 2);
;         const float y0 = (outv[t][0] - st[0]) * st[1] * lg[0] + lb[0], y1 = (outv[t][1] - st[0]) * st[1] * lg[1] + lb[1];
;         __builtin_nontemporal_store(pk_bf16(bf_lo(zz[t]) * siluf_(y0), bf_hi(zz[t]) * siluf_(y1)), (unsigned*)(SZB + (size_t)(t0 + t) * 1024 + c2));
;     }
.Lc31_nostat:
	s_waitcnt lgkmcnt(0)
	s_barrier
	s_waitcnt vmcnt(0)
	s_add_u32 s100, s28, s52
	s_addc_u32 s101, s29, s53
	ds_read_b128 v[228:231], v254 offset:1024
	ds_read_b128 v[232:235], v254 offset:1040
	ds_read_b128 v[236:239], v254 offset:1056
	ds_read_b128 v[240:243], v254 offset:1072
	s_waitcnt lgkmcnt(0)
	v_pk_add_f32 v[154:155], v[154:155], v[228:229] op_sel_hi:[1,0] neg_lo:[0,1] neg_hi:[0,1]
	v_pk_add_f32 v[156:157], v[156:157], v[230:231] op_sel_hi:[1,0] neg_lo:[0,1] neg_hi:[0,1]
	v_pk_mul_f32 v[154:155], v[228:229], v[154:155] op_sel:[1,0]
	v_pk_mul_f32 v[156:157], v[230:231], v[156:157] op_sel:[1,0]
	v_pk_fma_f32 v[154:155], v[154:155], v[220:221], v[222:223]
	v_pk_fma_f32 v[156:157], v[156:157], v[220:221], v[222:223]
	v_pk_mul_f32 v[244:245], v[154:155], s[54:55] op_sel_hi:[1,0]
	v_pk_mul_f32 v[248:249], v[156:157], s[54:55] op_sel_hi:[1,0]
	v_lshlrev_b32_e32 v246, 16, v202
	v_lshlrev_b32_e32 v250, 16, v203
	v_exp_f32_e32 v244, v244
	v_exp_f32_e32 v248, v248
	v_exp_f32_e32 v245, v245
	v_exp_f32_e32 v249, v249
	v_and_b32_e32 v247, 0xffff0000, v202
	v_and_b32_e32 v251, 0xffff0000, v203
	v_add_f32_e32 v244, 1.0, v244
	v_add_f32_e32 v248, 1.0, v248
	v_add_f32_e32 v245, 1.0, v245
	v_add_f32_e32 v249, 1.0, v249
	v_rcp_f32_e32 v244, v244
	v_rcp_f32_e32 v248, v248
	v_rcp_f32_e32 v245, v245
	v_rcp_f32_e32 v249, v249
	v_pk_mul_f32 v[246:247], v[246:247], v[154:155]
	v_pk_mul_f32 v[250:251], v[250:251], v[156:157]
	v_pk_mul_f32 v[246:247], v[246:247], v[244:245]
	v_pk_mul_f32 v[250:251], v[250:251], v[248:249]
	s_nop 0
	v_cvt_pk_bf16_f32 v244, v246, v247
	v_cvt_pk_bf16_f32 v248, v250, v251
	global_store_dword v226, v244, s[100:101] nt
	global_store_dword v226, v248, s[100:101] offset:2048 nt
	s_add_u32 s100, s100, 0x1000
	s_addc_u32 s101, s101, 0
	v_pk_add_f32 v[158:159], v[158:159], v[232:233] op_sel_hi:[1,0] neg_lo:[0,1] neg_hi:[0,1]
	v_pk_add_f32 v[160:161], v[160:161], v[234:235] op_sel_hi:[1,0] neg_lo:[0,1] neg_hi:[0,1]
	v_pk_mul_f32 v[158:159], v[232:233], v[158:159] op_sel:[1,0]
	v_pk_mul_f32 v[160:161], v[234:235], v[160:161] op_sel:[1,0]
	v_pk_fma_f32 v[158:159], v[158:159], v[220:221], v[222:223]
	v_pk_fma_f32 v[160:161], v[160:161], v[220:221], v[222:223]
	v_pk_mul_f32 v[244:245], v[158:159], s[54:55] op_sel_hi:[1,0]
	v_pk_mul_f32 v[248:249], v[160:161], s[54:55] op_sel_hi:[1,0]
	v_lshlrev_b32_e32 v246, 16, v204
	v_lshlrev_b32_e32 v250, 16, v205
	v_exp_f32_e32 v244, v244
	v_exp_f32_e32 v248, v248
	v_exp_f32_e32 v245, v245
	v_exp_f32_e32 v249, v249
	v_and_b32_e32 v247, 0xffff0000, v204
	v_and_b32_e32 v251, 0xffff0000, v205
	v_add_f32_e32 v244, 1.0, v244
	v_add_f32_e32 v248, 1.0, v248
	v_add_f32_e32 v245, 1.0, v245
	v_add_f32_e32 v249, 1.0, v249
	v_rcp_f32_e32 v244, v244
	v_rcp_f32_e32 v248, v248
	v_rcp_f32_e32 v245, v245
	v_rcp_f32_e32 v249, v249
	v_pk_mul_f32 v[246:247], v[246:247], v[158:159]
	v_pk_mul_f32 v[250:251], v[250:251], v[160:161]
	v_pk_mul_f32 v[246:247], v[246:247], v[244:245]
	v_pk_mul_f32 v[250:251], v[250:251], v[248:249]
	s_nop 0
	v_cvt_pk_bf16_f32 v244, v246, v247
	v_cvt_pk_bf16_f32 v248, v250, v251
	global_store_dword v226, v244, s[100:101] nt
	global_store_dword v226, v248, s[100:101] offset:2048 nt
	s_add_u32 s100, s100, 0x1000
	s_addc_u32 s101, s101, 0
	v_pk_add_f32 v[162:163], v[162:163], v[236:237] op_sel_hi:[1,0] neg_lo:[0,1] neg_hi:[0,1]
	v_pk_add_f32 v[164:165], v[164:165], v[238:239] op_sel_hi:[1,0] neg_lo:[0,1] neg_hi:[0,1]
	v_pk_mul_f32 v[162:163], v[236:237], v[162:163] op_sel:[1,0]
	v_pk_mul_f32 v[164:165], v[238:239], v[164:165] op_sel:[1,0]
	v_pk_fma_f32 v[162:163], v[162:163], v[220:221], v[222:223]
	v_pk_fma_f32 v[164:165], v[164:165], v[220:221], v[222:223]
	v_pk_mul_f32 v[244:245], v[162:163], s[54:55] op_sel_hi:[1,0]
	v_pk_mul_f32 v[248:249], v[164:165], s[54:55] op_sel_hi:[1,0]
	v_lshlrev_b32_e32 v246, 16, v206
	v_lshlrev_b32_e32 v250, 16, v207
	v_exp_f32_e32 v244, v244
	v_exp_f32_e32 v248, v248
	v_exp_f32_e32 v245, v245
	v_exp_f32_e32 v249, v249
	v_and_b32_e32 v247, 0xffff0000, v206
	v_and_b32_e32 v251, 0xffff0000, v207
	v_add_f32_e32 v244, 1.0, v244
	v_add_f32_e32 v248, 1.0, v248
	v_add_f32_e32 v245, 1.0, v245
	v_add_f32_e32 v249, 1.0, v249
	v_rcp_f32_e32 v244, v244
	v_rcp_f32_e32 v248, v248
	v_rcp_f32_e32 v245, v245
	v_rcp_f32_e32 v249, v249
	v_pk_mul_f32 v[246:247], v[246:247], v[162:163]
	v_pk_mul_f32 v[250:251], v[250:251], v[164:165]
	v_pk_mul_f32 v[246:247], v[246:247], v[244:245]
	v_pk_mul_f32 v[250:251], v[250:251], v[248:249]
	s_nop 0
	v_cvt_pk_bf16_f32 v244, v246, v247
	v_cvt_pk_bf16_f32 v248, v250, v251
	global_store_dword v226, v244, s[100:101] nt
	global_store_dword v226, v248, s[100:101] offset:2048 nt
	s_add_u32 s100, s100, 0x1000
	s_addc_u32 s101, s101, 0
	v_pk_add_f32 v[166:167], v[166:167], v[240:241] op_sel_hi:[1,0] neg_lo:[0,1] neg_hi:[0,1]
	v_pk_add_f32 v[168:169], v[168:169], v[242:243] op_sel_hi:[1,0] neg_lo:[0,1] neg_hi:[0,1]
	v_pk_mul_f32 v[166:167], v[240:241], v[166:167] op_sel:[1,0]
	v_pk_mul_f32 v[168:169], v[242:243], v[168:169] op_sel:[1,0]
	v_pk_fma_f32 v[166:167], v[166:167], v[220:221], v[222:223]
	v_pk_fma_f32 v[168:169], v[168:169], v[220:221], v[222:223]
	v_pk_mul_f32 v[244:245], v[166:167], s[54:55] op_sel_hi:[1,0]
	v_pk_mul_f32 v[248:249], v[168:169], s[54:55] op_sel_hi:[1,0]
	v_lshlrev_b32_e32 v246, 16, v208
	v_lshlrev_b32_e32 v250, 16, v209
	v_exp_f32_e32 v244, v244
	v_exp_f32_e32 v248, v248
	v_exp_f32_e32 v245, v245
	v_exp_f32_e32 v249, v249
	v_and_b32_e32 v247, 0xffff0000, v208
	v_and_b32_e32 v251, 0xffff0000, v209
	v_add_f32_e32 v244, 1.0, v244
	v_add_f32_e32 v248, 1.0, v248
	v_add_f32_e32 v245, 1.0, v245
	v_add_f32_e32 v249, 1.0, v249
	v_rcp_f32_e32 v244, v244
	v_rcp_f32_e32 v248, v248
	v_rcp_f32_e32 v245, v245
	v_rcp_f32_e32 v249, v249
	v_pk_mul_f32 v[246:247], v[246:247], v[166:167]
	v_pk_mul_f32 v[250:251], v[250:251], v[168:169]
	v_pk_mul_f32 v[246:247], v[246:247], v[244:245]
	v_pk_mul_f32 v[250:251], v[250:251], v[248:249]
	s_nop 0
	v_cvt_pk_bf16_f32 v244, v246, v247
	v_cvt_pk_bf16_f32 v248, v250, v251
	global_store_dword v226, v244, s[100:101] nt
	global_store_dword v226, v248, s[100:101] offset:2048 nt
	s_add_u32 s100, s100, 0x1000
	s_addc_u32 s101, s101, 0
	ds_read_b128 v[228:231], v254 offset:1088
	ds_read_b128 v[232:235], v254 offset:1104
	ds_read_b128 v[236:239], v254 offset:1120
	ds_read_b128 v[240:243], v254 offset:1136
	s_waitcnt lgkmcnt(0)
; #define LAS __attribute__((address_space(3)))
; __device__ __forceinline__ float bf_lo(unsigned u) { return __uint_as_float(u << 16); }
; template <int PH> ...
;     ...
;     for (int t = 0; t < 16; ++t) {
;         const f32x2 st = *(const LAS f32x2*)(stats + t * 2);
;         const float y0 = (outv[t][0] - st[0]) * st[1] * lg[0] + lb[0], y1 = (outv[t][1] - st[0]) * st[1] * lg[1] + lb[1];
;         __builtin_nontemporal_store(pk_bf16(bf_lo(zz[t]) * siluf_(y0), bf_hi(zz[t]) * siluf_(y1)), (unsigned*)(SZB + (size_t)(t0 + t) * 1024 + c2));
;     }
; __device__ __forceinline__ void conv31_phase(LAS unsigned char* lds, const bf16_t* GLU, bf16_t* SZB, const float* cw, const float* cb, const float* lng, const float* lnb, int G, int c, const int widx) {
;     ...
;     for (int run = c; run < NTOK / 128; run += G) {
;         const int T0 = run * 128, tpos = T0 & (SEQ - 1);
;         __syncthreads();
; #pragma unroll
;         for (int h = 0; h < 2; ++h) {
;             int tf = tid; asm volatile("" : "+v"(tf));
;             u32x4 tv[6];
; #pragma unroll
;             for (int q = 0; q < 6; ++q) { const int i = tf + (h * 6 + q) * 512, r = (i >> 7) < 46 ? (i >> 7) : 45; const int gr = (tpos - 30 + r >= 0) ? (T0 - 30 + r) : T0;
;                 tv[q] = *(const u32x4*)(GLU + (size_t)gr * 1024 + (i & 127) * 8); }
; #pragma unroll
;             for (int q = 0; q < 6; ++q) { const int i = tf + (h * 6 + q) * 512, r = i >> 7;
;                 if (r < 46) *(LAS u32x4*)(lds + ((34 + r) & 63) * 2048 + (i & 127) * 16) = (tpos - 30 + r >= 0) ? tv[q] : (u32x4){0u, 0u, 0u, 0u}; }
;         }
;         __syncthreads();
;         conv31_chunk<0>(lds, red, stats, GLU, SZB, cw, cb, lng, lnb, T0, true, tid);
;         conv31_chunk<1>(lds, red, stats, GLU, SZB, cw, cb, lng, lnb, T0 + 16, true, tid);
;         conv31_chunk<2>(lds, red, stats, GLU, SZB, cw, cb, lng, lnb, T0 + 32, true, tid);
;         conv31_chunk<3>(lds, red, stats, GLU, SZB, cw, cb, lng, lnb, T0 + 48, true, tid);
;         conv31_chunk<0>(lds, red, stats, GLU, SZB, cw, cb, lng, lnb, T0 + 64, true, tid);
;         conv31_chunk<1>(lds, red, stats, GLU, SZB, cw, cb, lng, lnb, T0 + 80, true, tid);
;         conv31_chunk<2>(lds, red, stats, GLU, SZB, cw, cb, lng, lnb, T0 + 96, true, tid);
;         conv31_chunk<3>(lds, red, stats, GLU, SZB, cw, cb, lng, lnb, T0 + 112, false, tid);
	v_pk_add_f32 v[170:171], v[170:171], v[228:229] op_sel_hi:[1,0] neg_lo:[0,1] neg_hi:[0,1]
	v_pk_add_f32 v[172:173], v[172:173], v[230:231] op_sel_hi:[1,0] neg_lo:[0,1] neg_hi:[0,1]
	v_pk_mul_f32 v[170:171], v[228:229], v[170:171] op_sel:[1,0]
	v_pk_mul_f32 v[172:173], v[230:231], v[172:173] op_sel:[1,0]
	v_pk_fma_f32 v[170:171], v[170:171], v[220:221], v[222:223]
	v_pk_fma_f32 v[172:173], v[172:173], v[220:221], v[222:223]
	v_pk_mul_f32 v[244:245], v[170:171], s[54:55] op_sel_hi:[1,0]
	v_pk_mul_f32 v[248:249], v[172:173], s[54:55] op_sel_hi:[1,0]
	v_lshlrev_b32_e32 v246, 16, v210
	v_lshlrev_b32_e32 v250, 16, v211
	v_exp_f32_e32 v244, v244
	v_exp_f32_e32 v248, v248
	v_exp_f32_e32 v245, v245
	v_exp_f32_e32 v249, v249
	v_and_b32_e32 v247, 0xffff0000, v210
	v_and_b32_e32 v251, 0xffff0000, v211
	v_add_f32_e32 v244, 1.0, v244
	v_add_f32_e32 v248, 1.0, v248
	v_add_f32_e32 v245, 1.0, v245
	v_add_f32_e32 v249, 1.0, v249
	v_rcp_f32_e32 v244, v244
	v_rcp_f32_e32 v248, v248
	v_rcp_f32_e32 v245, v245
	v_rcp_f32_e32 v249, v249
	v_pk_mul_f32 v[246:247], v[246:247], v[170:171]
	v_pk_mul_f32 v[250:251], v[250:251], v[172:173]
	v_pk_mul_f32 v[246:247], v[246:247], v[244:245]
	v_pk_mul_f32 v[250:251], v[250:251], v[248:249]
	s_nop 0
	v_cvt_pk_bf16_f32 v244, v246, v247
	v_cvt_pk_bf16_f32 v248, v250, v251
	global_store_dword v226, v244, s[100:101] nt
	global_store_dword v226, v248, s[100:101] offset:2048 nt
	s_add_u32 s100, s100, 0x1000
	s_addc_u32 s101, s101, 0
	v_pk_add_f32 v[174:175], v[174:175], v[232:233] op_sel_hi:[1,0] neg_lo:[0,1] neg_hi:[0,1]
	v_pk_add_f32 v[176:177], v[176:177], v[234:235] op_sel_hi:[1,0] neg_lo:[0,1] neg_hi:[0,1]
	v_pk_mul_f32 v[174:175], v[232:233], v[174:175] op_sel:[1,0]
	v_pk_mul_f32 v[176:177], v[234:235], v[176:177] op_sel:[1,0]
	v_pk_fma_f32 v[174:175], v[174:175], v[220:221], v[222:223]
	v_pk_fma_f32 v[176:177], v[176:177], v[220:221], v[222:223]
	v_pk_mul_f32 v[244:245], v[174:175], s[54:55] op_sel_hi:[1,0]
	v_pk_mul_f32 v[248:249], v[176:177], s[54:55] op_sel_hi:[1,0]
	v_lshlrev_b32_e32 v246, 16, v212
	v_lshlrev_b32_e32 v250, 16, v213
	v_exp_f32_e32 v244, v244
	v_exp_f32_e32 v248, v248
	v_exp_f32_e32 v245, v245
	v_exp_f32_e32 v249, v249
	v_and_b32_e32 v247, 0xffff0000, v212
	v_and_b32_e32 v251, 0xffff0000, v213
	v_add_f32_e32 v244, 1.0, v244
	v_add_f32_e32 v248, 1.0, v248
	v_add_f32_e32 v245, 1.0, v245
	v_add_f32_e32 v249, 1.0, v249
	v_rcp_f32_e32 v244, v244
	v_rcp_f32_e32 v248, v248
	v_rcp_f32_e32 v245, v245
	v_rcp_f32_e32 v249, v249
	v_pk_mul_f32 v[246:247], v[246:247], v[174:175]
	v_pk_mul_f32 v[250:251], v[250:251], v[176:177]
	v_pk_mul_f32 v[246:247], v[246:247], v[244:245]
	v_pk_mul_f32 v[250:251], v[250:251], v[248:249]
	s_nop 0
	v_cvt_pk_bf16_f32 v244, v246, v247
	v_cvt_pk_bf16_f32 v248, v250, v251
	global_store_dword v226, v244, s[100:101] nt
	global_store_dword v226, v248, s[100:101] offset:2048 nt
	s_add_u32 s100, s100, 0x1000
	s_addc_u32 s101, s101, 0
	v_pk_add_f32 v[178:179], v[178:179], v[236:237] op_sel_hi:[1,0] neg_lo:[0,1] neg_hi:[0,1]
	v_pk_add_f32 v[180:181], v[180:181], v[238:239] op_sel_hi:[1,0] neg_lo:[0,1] neg_hi:[0,1]
	v_pk_mul_f32 v[178:179], v[236:237], v[178:179] op_sel:[1,0]
	v_pk_mul_f32 v[180:181], v[238:239], v[180:181] op_sel:[1,0]
	v_pk_fma_f32 v[178:179], v[178:179], v[220:221], v[222:223]
	v_pk_fma_f32 v[180:181], v[180:181], v[220:221], v[222:223]
	v_pk_mul_f32 v[244:245], v[178:179], s[54:55] op_sel_hi:[1,0]
	v_pk_mul_f32 v[248:249], v[180:181], s[54:55] op_sel_hi:[1,0]
	v_lshlrev_b32_e32 v246, 16, v214
	v_lshlrev_b32_e32 v250, 16, v215
	v_exp_f32_e32 v244, v244
	v_exp_f32_e32 v248, v248
	v_exp_f32_e32 v245, v245
	v_exp_f32_e32 v249, v249
	v_and_b32_e32 v247, 0xffff0000, v214
	v_and_b32_e32 v251, 0xffff0000, v215
	v_add_f32_e32 v244, 1.0, v244
	v_add_f32_e32 v248, 1.0, v248
	v_add_f32_e32 v245, 1.0, v245
	v_add_f32_e32 v249, 1.0, v249
	v_rcp_f32_e32 v244, v244
	v_rcp_f32_e32 v248, v248
	v_rcp_f32_e32 v245, v245
	v_rcp_f32_e32 v249, v249
	v_pk_mul_f32 v[246:247], v[246:247], v[178:179]
	v_pk_mul_f32 v[250:251], v[250:251], v[180:181]
	v_pk_mul_f32 v[246:247], v[246:247], v[244:245]
	v_pk_mul_f32 v[250:251], v[250:251], v[248:249]
	s_nop 0
	v_cvt_pk_bf16_f32 v244, v246, v247
	v_cvt_pk_bf16_f32 v248, v250, v251
	global_store_dword v226, v244, s[100:101] nt
	global_store_dword v226, v248, s[100:101] offset:2048 nt
	s_add_u32 s100, s100, 0x1000
	s_addc_u32 s101, s101, 0
	v_pk_add_f32 v[182:183], v[182:183], v[240:241] op_sel_hi:[1,0] neg_lo:[0,1] neg_hi:[0,1]
	v_pk_add_f32 v[184:185], v[184:185], v[242:243] op_sel_hi:[1,0] neg_lo:[0,1] neg_hi:[0,1]
	v_pk_mul_f32 v[182:183], v[240:241], v[182:183] op_sel:[1,0]
	v_pk_mul_f32 v[184:185], v[242:243], v[184:185] op_sel:[1,0]
	v_pk_fma_f32 v[182:183], v[182:183], v[220:221], v[222:223]
	v_pk_fma_f32 v[184:185], v[184:185], v[220:221], v[222:223]
	v_pk_mul_f32 v[244:245], v[182:183], s[54:55] op_sel_hi:[1,0]
	v_pk_mul_f32 v[248:249], v[184:185], s[54:55] op_sel_hi:[1,0]
	v_lshlrev_b32_e32 v246, 16, v216
	v_lshlrev_b32_e32 v250, 16, v217
	v_exp_f32_e32 v244, v244
	v_exp_f32_e32 v248, v248
	v_exp_f32_e32 v245, v245
	v_exp_f32_e32 v249, v249
	v_and_b32_e32 v247, 0xffff0000, v216
	v_and_b32_e32 v251, 0xffff0000, v217
	v_add_f32_e32 v244, 1.0, v244
	v_add_f32_e32 v248, 1.0, v248
	v_add_f32_e32 v245, 1.0, v245
	v_add_f32_e32 v249, 1.0, v249
	v_rcp_f32_e32 v244, v244
	v_rcp_f32_e32 v248, v248
	v_rcp_f32_e32 v245, v245
	v_rcp_f32_e32 v249, v249
	v_pk_mul_f32 v[246:247], v[246:247], v[182:183]
	v_pk_mul_f32 v[250:251], v[250:251], v[184:185]
	v_pk_mul_f32 v[246:247], v[246:247], v[244:245]
	v_pk_mul_f32 v[250:251], v[250:251], v[248:249]
	s_nop 0
	v_cvt_pk_bf16_f32 v244, v246, v247
	v_cvt_pk_bf16_f32 v248, v250, v251
	global_store_dword v226, v244, s[100:101] nt
	global_store_dword v226, v248, s[100:101] offset:2048 nt
	s_add_u32 s100, s100, 0x1000
	s_addc_u32 s101, s101, 0
	s_cmp_eq_u32 s7, 7
	s_cbranch_scc1 .LBB0_458
; #define LAS __attribute__((address_space(3)))
; template <int PH> ...
;     ...
;         for (int q = 0; q < 4; ++q) { const int i = tid + q * 512; *(LAS u32x4*)(lds + ((34 + 16 * PH + 46 + (i >> 7)) & 63) * 2048 + (i & 127) * 16) = nx[q]; }
; __device__ __forceinline__ void conv31_phase(LAS unsigned char* lds, const bf16_t* GLU, bf16_t* SZB, const float* cw, const float* cb, const float* lng, const float* lnb, int G, int c, const int widx) {
;     ...
;         conv31_chunk<0>(lds, red, stats, GLU, SZB, cw, cb, lng, lnb, T0, true, tid);
;         conv31_chunk<1>(lds, red, stats, GLU, SZB, cw, cb, lng, lnb, T0 + 16, true, tid);
;         conv31_chunk<2>(lds, red, stats, GLU, SZB, cw, cb, lng, lnb, T0 + 32, true, tid);
;         conv31_chunk<3>(lds, red, stats, GLU, SZB, cw, cb, lng, lnb, T0 + 48, true, tid);
;         conv31_chunk<0>(lds, red, stats, GLU, SZB, cw, cb, lng, lnb, T0 + 64, true, tid);
;         conv31_chunk<1>(lds, red, stats, GLU, SZB, cw, cb, lng, lnb, T0 + 80, true, tid);
;         conv31_chunk<2>(lds, red, stats, GLU, SZB, cw, cb, lng, lnb, T0 + 96, true, tid);
;         conv31_chunk<3>(lds, red, stats, GLU, SZB, cw, cb, lng, lnb, T0 + 112, false, tid);
	v_mov_b64_e32 v[0:1], v[32:33]
	v_mov_b64_e32 v[2:3], v[34:35]
	v_mov_b64_e32 v[4:5], v[36:37]
	v_mov_b64_e32 v[6:7], v[38:39]
	v_mov_b64_e32 v[8:9], v[40:41]
	v_mov_b64_e32 v[10:11], v[42:43]
	v_mov_b64_e32 v[12:13], v[44:45]
	v_mov_b64_e32 v[14:15], v[46:47]
	v_mov_b64_e32 v[16:17], v[48:49]
	v_mov_b64_e32 v[18:19], v[50:51]
	v_mov_b64_e32 v[20:21], v[52:53]
	v_mov_b64_e32 v[22:23], v[54:55]
	v_mov_b64_e32 v[24:25], v[56:57]
	v_mov_b64_e32 v[26:27], v[58:59]
	v_mov_b64_e32 v[28:29], v[60:61]
	v_mov_b64_e32 v[30:31], v[62:63]
	v_mov_b64_e32 v[32:33], v[64:65]
	v_mov_b64_e32 v[34:35], v[66:67]
	v_mov_b64_e32 v[36:37], v[68:69]
	v_mov_b64_e32 v[38:39], v[70:71]
	v_mov_b64_e32 v[40:41], v[72:73]
	v_mov_b64_e32 v[42:43], v[74:75]
	v_mov_b64_e32 v[44:45], v[76:77]
	v_mov_b64_e32 v[46:47], v[78:79]
	v_mov_b64_e32 v[48:49], v[80:81]
	v_mov_b64_e32 v[50:51], v[82:83]
	v_mov_b64_e32 v[52:53], v[84:85]
	v_mov_b64_e32 v[54:55], v[86:87]
	v_mov_b64_e32 v[56:57], v[88:89]
	v_mov_b64_e32 v[58:59], v[90:91]
	v_and_b32_e32 v61, 0xffff0000, v186
	v_lshlrev_b32_e32 v60, 16, v186
	v_and_b32_e32 v63, 0xffff0000, v187
	v_lshlrev_b32_e32 v62, 16, v187
	v_and_b32_e32 v65, 0xffff0000, v188
	v_lshlrev_b32_e32 v64, 16, v188
	v_and_b32_e32 v67, 0xffff0000, v189
	v_lshlrev_b32_e32 v66, 16, v189
	v_and_b32_e32 v69, 0xffff0000, v190
	v_lshlrev_b32_e32 v68, 16, v190
	v_and_b32_e32 v71, 0xffff0000, v191
	v_lshlrev_b32_e32 v70, 16, v191
	v_and_b32_e32 v73, 0xffff0000, v192
	v_lshlrev_b32_e32 v72, 16, v192
	v_and_b32_e32 v75, 0xffff0000, v193
	v_lshlrev_b32_e32 v74, 16, v193
	v_and_b32_e32 v77, 0xffff0000, v194
	v_lshlrev_b32_e32 v76, 16, v194
	v_and_b32_e32 v79, 0xffff0000, v195
	v_lshlrev_b32_e32 v78, 16, v195
	v_and_b32_e32 v81, 0xffff0000, v196
	v_lshlrev_b32_e32 v80, 16, v196
	v_and_b32_e32 v83, 0xffff0000, v197
	v_lshlrev_b32_e32 v82, 16, v197
	v_and_b32_e32 v85, 0xffff0000, v198
	v_lshlrev_b32_e32 v84, 16, v198
	v_and_b32_e32 v87, 0xffff0000, v199
	v_lshlrev_b32_e32 v86, 16, v199
	v_and_b32_e32 v89, 0xffff0000, v200
	v_lshlrev_b32_e32 v88, 16, v200
	v_and_b32_e32 v91, 0xffff0000, v201
	v_lshlrev_b32_e32 v90, 16, v201
	s_add_i32 s7, s7, 1
	s_add_i32 s34, s34, 16
	s_branch .Lc31_chunk
